# prologue de-serialisation in b3 (mLSTM output phase): m_in, n-vector and 16 state-tile loads hoisted to item start as one batch with counted vmcnt
# baseline (speedup 1.0000x reference)
; DI unsigned pk2(float a, float b) { return pg8::cvt_pk_bf16(a, b); }
; DI float bf2f(bf16_t h) { return __uint_as_float((unsigned)h << 16); }
; DI float fexp(float x) { return ex2(x * LOG2E); }
; DI float log_sigmoid_f(float x) { return fminf(x, 0.f) - lg2(1.0f + fexp(-fabsf(x))) * 0.6931471805599453f; }
; DI void lds_wave_sync() { asm volatile("s_waitcnt lgkmcnt(0)" ::: "memory"); __builtin_amdgcn_wave_barrier(); }
; DI void b3_phase(const bf16_t* P, const bf16_t* BQ, const bf16_t* BK, const bf16_t* VtB, const float* DC, const float* SC, const float* gate_bias, const float* onorm, bf16_t* Y, unsigned char* lds, int tid) {
;     ...
;     const int bh = item >> 8, c = item & 255, b = bh >> 2, h = bh & 3, s0 = c * 64; const size_t tok0 = (size_t)b * SEQ + s0;
;     const float* dc = DC + ((size_t)bh * 256 + c) * 4160;
;     {
;       const float gf = bf2f(P[(tok0 + lane) * PLD + C_GF + h]) + gate_bias[4 + h], gi = bf2f(P[(tok0 + lane) * PLD + C_GI + h]) + gate_bias[h];
;       const float lf = log_sigmoid_f(gf), bcum = wave_scan_add(lf, lane), r = gi - bcum, pmax = wave_scan_max(r, lane);
;       const float m_in = SC[4096 + bh * 256 + c], mu = fmaxf(m_in, pmax);
;       R[lane] = r; MU[lane] = mu; SI[lane] = fexp(m_in - mu); EM[lane] = fexp(-bcum - mu); NV[lane] = dc[4096 + lane];
;     }
;     lds_wave_sync();
;     bf16x8 cfr[2][4];
; #pragma unroll
;     for (int eb = 0; eb < 2; ++eb)
; #pragma unroll
;       for (int ks = 0; ks < 4; ++ks) { const float* cp = dc + (32 * eb + r32) * 64 + 16 * ks + 8 * hi; const f32x4 ca = *(const f32x4*)cp, cb = *(const f32x4*)(cp + 4);
;         u32x4 o; o.x = pk2(ca.x, ca.y); o.y = pk2(ca.z, ca.w); o.z = pk2(cb.x, cb.y); o.w = pk2(cb.z, cb.w); cfr[eb][ks] = __builtin_bit_cast(bf16x8, o); }
.LBB0_890:
	v_ashrrev_i32_e32 v4, 10, v115
	v_ashrrev_i32_e32 v0, 8, v115
	v_ashrrev_i32_e32 v5, 31, v4
	v_and_b32_e32 v3, 0xff, v115
	v_lshlrev_b64 v[152:153], 14, v[4:5]
	v_ashrrev_i32_e32 v1, 31, v0
	v_lshl_or_b32 v156, v3, 6, v152
	v_lshlrev_b64 v[50:51], 8, v[0:1]
	v_and_b32_e32 v2, 3, v0
	v_or_b32_e32 v50, v50, v3
	v_mov_b64_e32 v[0:1], s[86:87]
	s_movk_i32 s2, 0x4100
	v_or_b32_e32 v3, v156, v116
	v_mov_b64_e32 v[154:155], s[80:81]
	v_mad_i64_i32 v[0:1], s[2:3], v50, s2, v[0:1]
	v_mad_u64_u32 v[4:5], s[2:3], v3, s82, v[154:155]
	v_mad_i32_i24 v5, v153, s82, v5
	v_lshlrev_b32_e32 v32, 1, v2
	v_lshl_add_u64 v[4:5], v[4:5], 0, v[32:33]
	s_movk_i32 s2, 0x1000
	v_add_co_u32_e32 v4, vcc, s2, v4
	v_lshlrev_b32_e32 v6, 2, v2
	s_nop 0
	v_addc_co_u32_e32 v5, vcc, 0, v5, vcc
	global_load_ushort v3, v[4:5], off offset:2568
	global_load_dword v7, v6, s[92:93] offset:16
	s_mov_b32 s2, 0xbfb8aa3b
	global_load_ushort v4, v[4:5], off offset:2560
	v_lshlrev_b32_e32 v32, 2, v116
	global_load_dword v5, v6, s[92:93]
	v_mov_b32_e32 v149, v33
	v_mov_b32_e32 v151, v33
	v_add_u32_e32 v14, 0x1000, v115
	v_ashrrev_i32_e32 v15, 31, v14
	v_lshl_add_u64 v[14:15], v[14:15], 2, s[88:89]
	global_load_dword v22, v[14:15], off
	v_lshl_add_u64 v[24:25], v[0:1], 0, v[32:33]
	v_add_co_u32_e32 v24, vcc, 0x4000, v24
	v_lshl_add_u64 v[192:193], v[0:1], 0, v[148:149]
	s_nop 0
	v_addc_co_u32_e32 v25, vcc, 0, v25, vcc
	global_load_dword v23, v[24:25], off
	v_lshl_add_u64 v[192:193], v[192:193], 0, v[150:151]
	s_nop 0
	global_load_dwordx4 v[204:207], v[192:193], off
	global_load_dwordx4 v[208:211], v[192:193], off offset:16
	global_load_dwordx4 v[212:215], v[192:193], off offset:64
	global_load_dwordx4 v[216:219], v[192:193], off offset:80
	global_load_dwordx4 v[220:223], v[192:193], off offset:128
	global_load_dwordx4 v[224:227], v[192:193], off offset:144
	global_load_dwordx4 v[228:231], v[192:193], off offset:192
	global_load_dwordx4 v[172:175], v[192:193], off offset:208
	v_add_co_u32_e32 v232, vcc, 0x2000, v192
	s_nop 1
	v_addc_co_u32_e32 v233, vcc, 0, v193, vcc
	s_nop 0
	global_load_dwordx4 v[176:179], v[232:233], off
	global_load_dwordx4 v[180:183], v[232:233], off offset:16
	global_load_dwordx4 v[184:187], v[232:233], off offset:64
	global_load_dwordx4 v[188:191], v[232:233], off offset:80
	global_load_dwordx4 v[34:37], v[232:233], off offset:128
	global_load_dwordx4 v[38:41], v[232:233], off offset:144
	global_load_dwordx4 v[42:45], v[232:233], off offset:192
	global_load_dwordx4 v[46:49], v[232:233], off offset:208
	v_or_b32_e32 v152, v156, v114
	v_lshlrev_b64 v[20:21], 9, v[152:153]
	v_lshlrev_b64 v[158:159], 13, v[50:51]
	v_or_b32_e32 v158, v158, v146
	v_lshl_add_u64 v[160:161], v[124:125], 0, v[158:159]
	v_or_b32_e32 v158, 0x1000, v158
	v_lshl_add_u64 v[168:169], v[124:125], 0, v[158:159]
	v_or_b32_e32 v156, v156, v134
	v_mov_b32_e32 v157, v153
	s_waitcnt vmcnt(21)
	v_lshlrev_b32_e32 v3, 16, v3
	s_waitcnt vmcnt(20)
	v_add_f32_e32 v3, v7, v3
	s_waitcnt vmcnt(19)
	v_lshlrev_b32_e32 v4, 16, v4
	s_waitcnt vmcnt(18)
	v_add_f32_e32 v4, v5, v4
	v_min_f32_e32 v5, 0, v3
	v_mul_f32_e64 v3, |v3|, s2
	v_exp_f32_e32 v3, v3
	s_movk_i32 s2, 0x4000
	v_add_f32_e32 v3, 1.0, v3
	v_log_f32_e32 v3, v3
	s_nop 0
	v_fmac_f32_e32 v5, 0xbf317218, v3
	ds_bpermute_b32 v3, v117, v5
	s_waitcnt lgkmcnt(0)
	v_add_f32_e32 v3, v5, v3
	v_cndmask_b32_e64 v3, v3, v5, s[4:5]
	ds_bpermute_b32 v5, v123, v3
	s_waitcnt lgkmcnt(0)
	v_add_f32_e32 v5, v3, v5
	v_cndmask_b32_e64 v3, v5, v3, s[6:7]
	ds_bpermute_b32 v5, v127, v3
	s_waitcnt lgkmcnt(0)
	v_add_f32_e32 v5, v3, v5
	v_cndmask_b32_e64 v3, v5, v3, s[8:9]
	ds_bpermute_b32 v5, v129, v3
	s_waitcnt lgkmcnt(0)
	v_add_f32_e32 v5, v3, v5
	v_cndmask_b32_e64 v3, v5, v3, s[10:11]
	ds_bpermute_b32 v5, v131, v3
	s_waitcnt lgkmcnt(0)
	v_add_f32_e32 v5, v3, v5
	v_cndmask_b32_e64 v3, v5, v3, s[12:13]
	ds_bpermute_b32 v5, v135, v3
	s_waitcnt lgkmcnt(0)
	v_add_f32_e32 v5, v3, v5
	v_cndmask_b32_e64 v3, v5, v3, s[14:15]
	v_sub_f32_e32 v6, v4, v3
	ds_bpermute_b32 v4, v117, v6
	s_waitcnt lgkmcnt(0)
	v_max_f32_e32 v4, v4, v4
	v_max_f32_e32 v4, v6, v4
	v_cndmask_b32_e64 v4, v4, v6, s[4:5]
	ds_bpermute_b32 v5, v123, v4
	s_waitcnt lgkmcnt(0)
	v_max_f32_e32 v5, v5, v5
	v_max_f32_e32 v5, v4, v5
	v_cndmask_b32_e64 v4, v5, v4, s[6:7]
	ds_bpermute_b32 v5, v127, v4
	s_waitcnt lgkmcnt(0)
	v_max_f32_e32 v5, v5, v5
	v_max_f32_e32 v5, v4, v5
	v_cndmask_b32_e64 v4, v5, v4, s[8:9]
	ds_bpermute_b32 v5, v129, v4
	s_waitcnt lgkmcnt(0)
	v_max_f32_e32 v5, v5, v5
	v_max_f32_e32 v5, v4, v5
	v_cndmask_b32_e64 v4, v5, v4, s[10:11]
	ds_bpermute_b32 v5, v131, v4
	s_waitcnt lgkmcnt(0)
	v_max_f32_e32 v5, v5, v5
	v_max_f32_e32 v5, v4, v5
	v_cndmask_b32_e64 v4, v5, v4, s[12:13]
	ds_bpermute_b32 v5, v135, v4
	v_max_f32_e32 v7, v4, v4
	s_waitcnt lgkmcnt(0)
	v_max_f32_e32 v5, v5, v5
	v_max_f32_e32 v5, v7, v5
	v_cndmask_b32_e64 v7, v5, v4, s[14:15]
	v_max_f32_e32 v5, v7, v7
	v_add_u32_e32 v115, s20, v115
	s_waitcnt vmcnt(17)
	v_mov_b32_e32 v4, v22
	v_max_f32_e32 v7, v4, v4
	v_max_f32_e32 v5, v7, v5
	v_sub_f32_e32 v4, v4, v5
	v_sub_f32_e64 v3, -v3, v5
	v_mul_f32_e32 v4, 0x3fb8aa3b, v4
	v_mul_f32_e32 v3, 0x3fb8aa3b, v3
	v_exp_f32_e32 v4, v4
	v_exp_f32_e32 v3, v3
	ds_write2st64_b32 v137, v6, v5 offset1:1
	ds_write2st64_b32 v137, v4, v3 offset0:2 offset1:3
	v_lshlrev_b32_e32 v32, 7, v2
	v_lshl_add_u64 v[98:99], v[118:119], 0, v[32:33]
	v_lshl_add_u64 v[162:163], v[120:121], 0, v[32:33]
	v_lshl_add_u64 v[170:171], v[162:163], 0, v[20:21]
	s_waitcnt vmcnt(16)
	ds_write_b32 v137, v23 offset:1024
	s_waitcnt lgkmcnt(0)
; DI unsigned pk2(float a, float b) { return pg8::cvt_pk_bf16(a, b); }
; DI float bflo(unsigned w) { return __uint_as_float(w << 16); }
; DI float bfhi(unsigned w) { return __uint_as_float(w & 0xffff0000u); }
; #define MFMA32(a, b, c) __builtin_amdgcn_mfma_f32_32x32x16_bf16((a), (b), (c), 0, 0, 0)
; DI void b3_phase(const bf16_t* P, const bf16_t* BQ, const bf16_t* BK, const bf16_t* VtB, const float* DC, const float* SC, const float* gate_bias, const float* onorm, bf16_t* Y, unsigned char* lds, int tid) {
;     ...
;     bf16x8 cfr[2][4];
; #pragma unroll
;     for (int eb = 0; eb < 2; ++eb)
; #pragma unroll
;       for (int ks = 0; ks < 4; ++ks) { const float* cp = dc + (32 * eb + r32) * 64 + 16 * ks + 8 * hi; const f32x4 ca = *(const f32x4*)cp, cb = *(const f32x4*)(cp + 4);
;         u32x4 o; o.x = pk2(ca.x, ca.y); o.y = pk2(ca.z, ca.w); o.z = pk2(cb.x, cb.y); o.w = pk2(cb.z, cb.w); cfr[eb][ks] = __builtin_bit_cast(bf16x8, o); }
; #pragma unroll
;     for (int tq = 0; tq < 2; ++tq) {
;       const int t = 32 * tq + r32; const float mu_t = MU[t], si_t = SI[t], em_t = EM[t];
;       bf16x8 qf[4]; float qn = 0.f;
; #pragma unroll
;       for (int ks = 0; ks < 4; ++ks) {
;         const u32x4 qw = *(const u32x4*)(BQ + (tok0 + t) * 256 + h * 64 + 16 * ks + 8 * hi); qf[ks] = __builtin_bit_cast(bf16x8, qw);
;         const f32x4 na = *(const f32x4*)(NV + 16 * ks + 8 * hi), nb = *(const f32x4*)(NV + 16 * ks + 8 * hi + 4);
;         qn += bflo(qw.x) * na.x + bfhi(qw.x) * na.y + bflo(qw.y) * na.z + bfhi(qw.y) * na.w + bflo(qw.z) * nb.x + bfhi(qw.z) * nb.y + bflo(qw.w) * nb.z + bfhi(qw.w) * nb.w;
;       }
;       qn += __shfl_xor(qn, 32);
;       f32x16 G[2], num[2];
; #pragma unroll
;       for (int eb = 0; eb < 2; ++eb) { G[eb] = splat16(0.f); num[eb] = splat16(0.f);
; #pragma unroll
;         for (int ks = 0; ks < 4; ++ks) G[eb] = MFMA32(cfr[eb][ks], qf[ks], G[eb]); }
;       float dsum = 0.f;
; #pragma unroll
;       for (int tk = 0; tk < 2; ++tk) {
;         if (tk <= tq) {
;           f32x16 S = splat16(0.f);
; #pragma unroll
;           for (int ks = 0; ks < 4; ++ks) { const bf16x8 kf = *(const bf16x8*)(BK + (tok0 + 32 * tk + r32) * 256 + h * 64 + 16 * ks + 8 * hi); S = MFMA32(kf, qf[ks], S); }
	v_readlane_b32 s2, v255, 51
	v_readlane_b32 s3, v255, 52
	ds_read2st64_b32 v[102:103], v147 offset0:1 offset1:2
	ds_read_b32 v149, v147 offset:768
	v_lshlrev_b32_e32 v0, 8, v2
	v_mov_b32_e32 v1, v33
	v_lshl_add_u64 v[100:101], s[94:95], 0, v[0:1]
	s_waitcnt vmcnt(0)
	v_cvt_pk_bf16_f32 v66, v204, v205
	v_cvt_pk_bf16_f32 v67, v206, v207
	v_cvt_pk_bf16_f32 v68, v208, v209
	v_cvt_pk_bf16_f32 v69, v210, v211
	v_cvt_pk_bf16_f32 v70, v212, v213
	v_cvt_pk_bf16_f32 v71, v214, v215
	v_cvt_pk_bf16_f32 v72, v216, v217
	v_cvt_pk_bf16_f32 v73, v218, v219
	v_cvt_pk_bf16_f32 v74, v220, v221
	v_cvt_pk_bf16_f32 v75, v222, v223
	v_cvt_pk_bf16_f32 v76, v224, v225
	v_cvt_pk_bf16_f32 v77, v226, v227
	v_cvt_pk_bf16_f32 v78, v228, v229
	v_cvt_pk_bf16_f32 v79, v230, v231
	v_cvt_pk_bf16_f32 v80, v172, v173
	v_cvt_pk_bf16_f32 v81, v174, v175
	v_cvt_pk_bf16_f32 v82, v176, v177
	v_cvt_pk_bf16_f32 v83, v178, v179
	v_cvt_pk_bf16_f32 v84, v180, v181
	v_cvt_pk_bf16_f32 v85, v182, v183
	v_cvt_pk_bf16_f32 v86, v184, v185
	v_cvt_pk_bf16_f32 v87, v186, v187
	v_cvt_pk_bf16_f32 v88, v188, v189
	v_cvt_pk_bf16_f32 v89, v190, v191
	v_cvt_pk_bf16_f32 v90, v34, v35
	v_cvt_pk_bf16_f32 v91, v36, v37
	v_cvt_pk_bf16_f32 v92, v38, v39
	v_cvt_pk_bf16_f32 v93, v40, v41
	v_cvt_pk_bf16_f32 v94, v42, v43
	v_cvt_pk_bf16_f32 v95, v44, v45
	v_cvt_pk_bf16_f32 v96, v46, v47
	v_cvt_pk_bf16_f32 v97, v48, v49
	v_lshl_add_u64 v[8:9], v[98:99], 0, v[20:21]
	global_load_dwordx4 v[16:19], v[8:9], off
	ds_read_b128 v[0:3], v139 offset:1024
	ds_read_b128 v[4:7], v139 offset:1040
	global_load_dwordx4 v[52:55], v[8:9], off offset:32
	s_waitcnt vmcnt(1)
	v_mfma_f32_32x32x16_bf16 v[34:49], v[66:69], v[16:19], 0
	v_lshlrev_b32_e32 v10, 16, v16
	s_waitcnt lgkmcnt(1)
	v_mul_f32_e32 v180, v0, v10
	v_and_b32_e32 v0, 0xffff0000, v16
	v_mul_f32_e32 v182, v1, v0
	v_lshlrev_b32_e32 v0, 16, v17
	v_mul_f32_e32 v184, v2, v0
	v_and_b32_e32 v0, 0xffff0000, v17
	v_mul_f32_e32 v186, v3, v0
	v_lshlrev_b32_e32 v0, 16, v18
	s_waitcnt lgkmcnt(0)
	v_mul_f32_e32 v188, v4, v0
	v_and_b32_e32 v0, 0xffff0000, v18
	v_mul_f32_e32 v190, v5, v0
	v_lshlrev_b32_e32 v0, 16, v19
	v_mul_f32_e32 v192, v6, v0
	v_and_b32_e32 v0, 0xffff0000, v19
	v_mul_f32_e32 v204, v7, v0
	ds_read_b128 v[0:3], v139 offset:1088
	ds_read_b128 v[4:7], v139 offset:1104
	global_load_dwordx4 v[56:59], v[8:9], off offset:64
	s_waitcnt vmcnt(1)
	v_and_b32_e32 v11, 0xffff0000, v52
	v_lshlrev_b32_e32 v10, 16, v52
	s_waitcnt lgkmcnt(1)
	v_mul_f32_e32 v12, v1, v11
	v_pk_fma_f32 v[0:1], v[0:1], v[10:11], v[12:13] op_sel_hi:[1,1,0]
	v_and_b32_e32 v11, 0xffff0000, v53
	v_lshlrev_b32_e32 v10, 16, v53
	v_pk_fma_f32 v[0:1], v[2:3], v[10:11], v[0:1]
	v_mul_f32_e32 v2, v3, v11
	v_pk_add_f32 v[0:1], v[2:3], v[0:1] op_sel_hi:[0,1]
	v_and_b32_e32 v3, 0xffff0000, v54
	v_lshlrev_b32_e32 v2, 16, v54
	s_waitcnt lgkmcnt(0)
	v_pk_fma_f32 v[0:1], v[4:5], v[2:3], v[0:1]
	v_mul_f32_e32 v2, v5, v3
	v_pk_add_f32 v[0:1], v[2:3], v[0:1] op_sel_hi:[0,1]
	v_and_b32_e32 v3, 0xffff0000, v55
	v_lshlrev_b32_e32 v2, 16, v55
	v_pk_fma_f32 v[0:1], v[6:7], v[2:3], v[0:1]
	v_mul_f32_e32 v2, v7, v3
	v_pk_add_f32 v[104:105], v[2:3], v[0:1] op_sel_hi:[0,1]
	ds_read_b128 v[0:3], v139 offset:1152
	ds_read_b128 v[4:7], v139 offset:1168
	global_load_dwordx4 v[60:63], v[8:9], off offset:96
	v_mfma_f32_32x32x16_bf16 v[34:49], v[70:73], v[52:55], v[34:49]
	s_waitcnt vmcnt(1)
	v_and_b32_e32 v11, 0xffff0000, v56
	v_lshlrev_b32_e32 v10, 16, v56
	s_waitcnt lgkmcnt(1)
	v_mul_f32_e32 v12, v1, v11
	v_pk_fma_f32 v[0:1], v[0:1], v[10:11], v[12:13] op_sel_hi:[1,1,0]
	v_and_b32_e32 v11, 0xffff0000, v57
	v_lshlrev_b32_e32 v10, 16, v57
	v_pk_fma_f32 v[0:1], v[2:3], v[10:11], v[0:1]
	v_mul_f32_e32 v2, v3, v11
	v_pk_add_f32 v[0:1], v[2:3], v[0:1] op_sel_hi:[0,1]
	v_and_b32_e32 v3, 0xffff0000, v58
	v_lshlrev_b32_e32 v2, 16, v58
	s_waitcnt lgkmcnt(0)
	v_pk_fma_f32 v[0:1], v[4:5], v[2:3], v[0:1]
	v_mul_f32_e32 v2, v5, v3
	v_pk_add_f32 v[0:1], v[2:3], v[0:1] op_sel_hi:[0,1]
	v_and_b32_e32 v3, 0xffff0000, v59
	v_lshlrev_b32_e32 v2, 16, v59
	v_pk_fma_f32 v[0:1], v[6:7], v[2:3], v[0:1]
	v_mul_f32_e32 v2, v7, v3
	v_pk_add_f32 v[106:107], v[2:3], v[0:1] op_sel_hi:[0,1]
	ds_read_b128 v[0:3], v139 offset:1216
	ds_read_b128 v[4:7], v139 offset:1232
	global_load_dwordx4 v[20:23], v[170:171], off
	global_load_dwordx4 v[110:113], v[170:171], off offset:32
	s_waitcnt vmcnt(2)
	v_and_b32_e32 v9, 0xffff0000, v60
	v_lshlrev_b32_e32 v8, 16, v60
	s_waitcnt lgkmcnt(1)
	v_mul_f32_e32 v10, v1, v9
	v_pk_fma_f32 v[0:1], v[0:1], v[8:9], v[10:11] op_sel_hi:[1,1,0]
	v_and_b32_e32 v9, 0xffff0000, v61
	v_lshlrev_b32_e32 v8, 16, v61
	v_pk_fma_f32 v[0:1], v[2:3], v[8:9], v[0:1]
	v_mul_f32_e32 v2, v3, v9
	v_pk_add_f32 v[0:1], v[2:3], v[0:1] op_sel_hi:[0,1]
	v_and_b32_e32 v3, 0xffff0000, v62
	v_lshlrev_b32_e32 v2, 16, v62
	s_waitcnt lgkmcnt(0)
	v_pk_fma_f32 v[0:1], v[4:5], v[2:3], v[0:1]
	v_mul_f32_e32 v2, v5, v3
	v_pk_add_f32 v[0:1], v[2:3], v[0:1] op_sel_hi:[0,1]
	v_and_b32_e32 v3, 0xffff0000, v63
	v_lshlrev_b32_e32 v2, 16, v63
	v_pk_fma_f32 v[0:1], v[6:7], v[2:3], v[0:1]
	v_mul_f32_e32 v2, v7, v3
	v_pk_add_f32 v[108:109], v[2:3], v[0:1] op_sel_hi:[0,1]
	v_mfma_f32_32x32x16_bf16 v[0:15], v[82:85], v[16:19], 0
	s_waitcnt vmcnt(1)
	v_mfma_f32_32x32x16_bf16 v[16:31], v[20:23], v[16:19], 0
	v_mfma_f32_32x32x16_bf16 v[0:15], v[86:89], v[52:55], v[0:15]
	s_waitcnt vmcnt(0)
	v_mfma_f32_32x32x16_bf16 v[16:31], v[110:113], v[52:55], v[16:31]
	global_load_dwordx4 v[52:55], v[170:171], off offset:64
	s_waitcnt vmcnt(0)
	v_mfma_f32_32x32x16_bf16 v[16:31], v[52:55], v[56:59], v[16:31]
	global_load_dwordx4 v[52:55], v[170:171], off offset:96
	v_mfma_f32_32x32x16_bf16 v[34:49], v[74:77], v[56:59], v[34:49]
	v_mfma_f32_32x32x16_bf16 v[0:15], v[90:93], v[56:59], v[0:15]
	s_waitcnt vmcnt(0)
; #define MFMA32(a, b, c) __builtin_amdgcn_mfma_f32_32x32x16_bf16((a), (b), (c), 0, 0, 0)
; DI float fexp(float x) { return ex2(x * LOG2E); }
; DI void b3_phase(const bf16_t* P, const bf16_t* BQ, const bf16_t* BK, const bf16_t* VtB, const float* DC, const float* SC, const float* gate_bias, const float* onorm, bf16_t* Y, unsigned char* lds, int tid) {
;     ...
;       for (int tk = 0; tk < 2; ++tk) {
;         if (tk <= tq) {
;           f32x16 S = splat16(0.f);
; #pragma unroll
;           for (int ks = 0; ks < 4; ++ks) { const bf16x8 kf = *(const bf16x8*)(BK + (tok0 + 32 * tk + r32) * 256 + h * 64 + 16 * ks + 8 * hi); S = MFMA32(kf, qf[ks], S); }
;           asm volatile("" ::: "memory");
; #pragma unroll
;           for (int g4 = 0; g4 < 4; ++g4) { const f32x4 rv = *(const f32x4*)(R + 32 * tk + 8 * g4 + 4 * hi);
; #pragma unroll
;             for (int j = 0; j < 4; ++j) { const int s = 32 * tk + 8 * g4 + 4 * hi + j; const float w = (s <= t) ? fexp(rv[j] - mu_t) : 0.f; const float val = S[4 * g4 + j] * w; dsum += val; S[4 * g4 + j] = val; } }
; #pragma unroll
;           for (int kk = 0; kk < 2; ++kk) { const bf16x8 pf = pack8(S, kk);
; #pragma unroll
;             for (int eb = 0; eb < 2; ++eb) { const bf16_t* vp = VtB + (((size_t)bh * 256 + c) * 64 + 32 * eb + r32) * 64 + 32 * tk + 16 * kk + 8 * hi;
;               const bf16x8 vf = *(const bf16x8*)vp; num[eb] = MFMA32(vf, pf, num[eb]); } }
;           asm volatile("" ::: "memory");
;         }
;       }
;       dsum += __shfl_xor(dsum, 32);
;       const float den = si_t * qn + dsum, inv = 1.0f / fmaxf(fabsf(den), em_t);
;       float ss = 0.f;
; #pragma unroll
;       for (int eb = 0; eb < 2; ++eb)
; #pragma unroll
;         for (int i = 0; i < 16; ++i) { const float hv = (num[eb][i] + si_t * G[eb][i]) * inv; num[eb][i] = hv; ss += hv * hv; }
	v_mfma_f32_32x32x16_bf16 v[16:31], v[52:55], v[60:63], v[16:31]
	ds_read_b128 v[52:55], v247
	ds_read_b128 v[56:59], v247 offset:32
	global_load_dwordx4 v[164:167], v[160:161], off offset:32
	s_waitcnt lgkmcnt(1)
	v_sub_f32_e32 v52, v52, v102
	v_mul_f32_e32 v52, 0x3fb8aa3b, v52
	v_exp_f32_e32 v52, v52
	v_mfma_f32_32x32x16_bf16 v[34:49], v[78:81], v[60:63], v[34:49]
	v_cndmask_b32_e64 v52, v52, 0, s[16:17]
	v_mfma_f32_32x32x16_bf16 v[0:15], v[94:97], v[60:63], v[0:15]
	s_nop 1
	v_mul_f32_e32 v60, v16, v52
	v_fma_f32 v61, v16, v52, 0
	v_sub_f32_e32 v16, v53, v102
	v_mul_f32_e32 v16, 0x3fb8aa3b, v16
	v_exp_f32_e32 v16, v16
	s_nop 0
	v_cndmask_b32_e64 v16, 0, v16, s[2:3]
	v_mul_f32_e32 v62, v17, v16
	v_fmac_f32_e32 v61, v17, v16
	v_sub_f32_e32 v16, v54, v102
	v_sub_f32_e32 v17, v55, v102
	v_mul_f32_e32 v16, 0x3fb8aa3b, v16
	v_mul_f32_e32 v17, 0x3fb8aa3b, v17
	v_exp_f32_e32 v16, v16
	v_exp_f32_e32 v17, v17
	v_cndmask_b32_e64 v16, v16, 0, s[22:23]
	v_cndmask_b32_e64 v17, v17, 0, s[18:19]
	v_pk_mul_f32 v[52:53], v[18:19], v[16:17]
	s_waitcnt lgkmcnt(0)
	v_sub_f32_e32 v17, v57, v102
	v_add_f32_e32 v16, v52, v61
	v_add_f32_e32 v18, v53, v16
	v_sub_f32_e32 v16, v56, v102
	v_mul_f32_e32 v16, 0x3fb8aa3b, v16
	v_mul_f32_e32 v17, 0x3fb8aa3b, v17
	v_exp_f32_e32 v16, v16
	v_exp_f32_e32 v17, v17
	v_cndmask_b32_e64 v16, v16, 0, s[26:27]
	v_cndmask_b32_e64 v17, v17, 0, s[24:25]
	v_pk_mul_f32 v[206:207], v[20:21], v[16:17]
	v_sub_f32_e32 v16, v58, v102
	v_sub_f32_e32 v17, v59, v102
	v_mul_f32_e32 v16, 0x3fb8aa3b, v16
	v_mul_f32_e32 v17, 0x3fb8aa3b, v17
	v_exp_f32_e32 v16, v16
	v_exp_f32_e32 v17, v17
	v_add_f32_e32 v183, v206, v18
	v_mov_b32_e32 v181, v207
	v_cndmask_b32_e64 v16, v16, 0, s[30:31]
	v_cndmask_b32_e64 v17, v17, 0, s[28:29]
	v_pk_mul_f32 v[208:209], v[22:23], v[16:17]
	global_load_dwordx4 v[20:23], v[160:161], off
	ds_read_b128 v[16:19], v247 offset:64
	v_mov_b32_e32 v185, v208
	v_mov_b32_e32 v187, v209
	s_waitcnt lgkmcnt(0)
	v_sub_f32_e32 v16, v16, v102
	v_sub_f32_e32 v17, v17, v102
	v_mul_f32_e32 v16, 0x3fb8aa3b, v16
	v_mul_f32_e32 v17, 0x3fb8aa3b, v17
	v_exp_f32_e32 v16, v16
	v_exp_f32_e32 v17, v17
	v_cndmask_b32_e64 v16, v16, 0, s[36:37]
	v_cndmask_b32_e64 v17, v17, 0, s[34:35]
	v_pk_mul_f32 v[210:211], v[24:25], v[16:17]
	v_sub_f32_e32 v16, v18, v102
	v_sub_f32_e32 v17, v19, v102
	v_mul_f32_e32 v16, 0x3fb8aa3b, v16
	v_mul_f32_e32 v17, 0x3fb8aa3b, v17
	v_exp_f32_e32 v16, v16
	v_exp_f32_e32 v17, v17
	v_cvt_pk_bf16_f32 v172, v210, v211
	v_mov_b32_e32 v189, v210
	v_cndmask_b32_e64 v16, v16, 0, s[40:41]
	v_cndmask_b32_e64 v17, v17, 0, s[38:39]
	v_pk_mul_f32 v[212:213], v[26:27], v[16:17]
	ds_read_b128 v[16:19], v247 offset:96
	v_cvt_pk_bf16_f32 v173, v212, v213
	v_mov_b32_e32 v191, v211
	v_mov_b32_e32 v193, v212
	v_mov_b32_e32 v205, v213
	s_waitcnt lgkmcnt(0)
	v_sub_f32_e32 v16, v16, v102
	v_sub_f32_e32 v17, v17, v102
	v_mul_f32_e32 v16, 0x3fb8aa3b, v16
	v_mul_f32_e32 v17, 0x3fb8aa3b, v17
	v_exp_f32_e32 v16, v16
	v_exp_f32_e32 v17, v17
	v_mov_b32_e32 v210, v103
	v_cndmask_b32_e64 v16, v16, 0, s[44:45]
	v_cndmask_b32_e64 v17, v17, 0, s[42:43]
	v_pk_mul_f32 v[110:111], v[28:29], v[16:17]
	v_sub_f32_e32 v16, v18, v102
	v_sub_f32_e32 v17, v19, v102
	v_mul_f32_e32 v16, 0x3fb8aa3b, v16
	v_mul_f32_e32 v17, 0x3fb8aa3b, v17
	v_exp_f32_e32 v16, v16
	v_exp_f32_e32 v17, v17
	v_cvt_pk_bf16_f32 v18, v206, v207
	v_cvt_pk_bf16_f32 v19, v208, v209
	v_cndmask_b32_e64 v16, v16, 0, s[48:49]
	v_cndmask_b32_e64 v17, v17, 0, s[46:47]
	v_pk_mul_f32 v[112:113], v[30:31], v[16:17]
	v_cvt_pk_bf16_f32 v16, v60, v62
	v_cvt_pk_bf16_f32 v17, v52, v53
	v_cvt_pk_bf16_f32 v174, v110, v111
	v_cvt_pk_bf16_f32 v175, v112, v113
	s_waitcnt vmcnt(0)
	v_mfma_f32_32x32x16_bf16 v[50:65], v[20:23], v[16:19], 0
	global_load_dwordx4 v[20:23], v[168:169], off
	v_mov_b32_e32 v105, v111
	v_mov_b32_e32 v107, v112
	v_mov_b32_e32 v109, v113
	v_max_f32_e32 v102, v149, v149
	v_mfma_f32_32x32x16_bf16 v[50:65], v[164:167], v[172:175], v[50:65]
	v_lshl_add_u64 v[166:167], v[132:133], 0, v[158:159]
	global_load_dwordx4 v[176:179], v[166:167], off
	v_lshlrev_b64 v[164:165], 9, v[156:157]
	s_waitcnt vmcnt(1)
	v_mfma_f32_32x32x16_bf16 v[16:31], v[20:23], v[16:19], 0
	s_nop 6
	v_fma_f32 v34, v210, v34, v50
	v_fma_f32 v35, v210, v35, v51
	v_fma_f32 v36, v210, v36, v52
	v_fma_f32 v37, v210, v37, v53
	v_fma_f32 v40, v210, v40, v56
	v_fma_f32 v41, v210, v41, v57
	v_pk_fma_f32 v[38:39], v[210:211], v[38:39], v[54:55] op_sel_hi:[0,1,1]
	v_pk_fma_f32 v[44:45], v[210:211], v[44:45], v[60:61] op_sel_hi:[0,1,1]
	v_pk_fma_f32 v[42:43], v[210:211], v[42:43], v[58:59] op_sel_hi:[0,1,1]
	v_pk_fma_f32 v[48:49], v[210:211], v[48:49], v[64:65] op_sel_hi:[0,1,1]
	s_waitcnt vmcnt(0)
	v_mfma_f32_32x32x16_bf16 v[16:31], v[176:179], v[172:175], v[16:31]
	v_add_f32_e64 v172, v180, v182
	v_add_f32_e64 v173, v181, v183
	v_mov_b32_e32 v174, v33
	v_add_f32_e64 v172, v184, v172
	v_add_f32_e64 v173, v185, v173
	v_mov_b32_e32 v175, v110
	v_pk_add_f32 v[172:173], v[186:187], v[172:173]
	v_pk_fma_f32 v[46:47], v[210:211], v[46:47], v[62:63] op_sel_hi:[0,1,1]
	v_pk_add_f32 v[172:173], v[188:189], v[172:173]
	s_nop 2
	v_pk_fma_f32 v[10:11], v[210:211], v[10:11], v[26:27] op_sel_hi:[0,1,1]
	v_pk_add_f32 v[172:173], v[190:191], v[172:173]
	v_pk_fma_f32 v[2:3], v[210:211], v[2:3], v[18:19] op_sel_hi:[0,1,1]
	v_pk_add_f32 v[172:173], v[192:193], v[172:173]
	v_pk_fma_f32 v[0:1], v[210:211], v[0:1], v[16:17] op_sel_hi:[0,1,1]
	v_pk_add_f32 v[172:173], v[204:205], v[172:173]
	v_pk_fma_f32 v[6:7], v[210:211], v[6:7], v[22:23] op_sel_hi:[0,1,1]
	v_pk_add_f32 v[172:173], v[174:175], v[172:173]
	v_lshlrev_b32_e32 v174, 1, v122
	v_pk_add_f32 v[104:105], v[104:105], v[172:173]
	v_mov_b32_e32 v175, v33
	v_pk_add_f32 v[104:105], v[106:107], v[104:105]
	v_pk_fma_f32 v[4:5], v[210:211], v[4:5], v[20:21] op_sel_hi:[0,1,1]
	v_pk_add_f32 v[104:105], v[108:109], v[104:105]
	ds_bpermute_b32 v106, v141, v104
	ds_bpermute_b32 v107, v141, v105
	v_pk_fma_f32 v[8:9], v[210:211], v[8:9], v[24:25] op_sel_hi:[0,1,1]
	v_lshlrev_b32_e32 v182, 1, v126
	v_mov_b32_e32 v183, v33
	v_lshlrev_b32_e32 v190, 1, v128
	s_waitcnt lgkmcnt(0)
; DI float bflo(unsigned w) { return __uint_as_float(w << 16); }
; DI float bfhi(unsigned w) { return __uint_as_float(w & 0xffff0000u); }
; DI float rcpf_(float x) { return __builtin_amdgcn_rcpf(x); }
; DI float fexp(float x) { return ex2(x * LOG2E); }
; DI void b3_phase(const bf16_t* P, const bf16_t* BQ, const bf16_t* BK, const bf16_t* VtB, const float* DC, const float* SC, const float* gate_bias, const float* onorm, bf16_t* Y, unsigned char* lds, int tid) {
;     ...
;       dsum += __shfl_xor(dsum, 32);
;       const float den = si_t * qn + dsum, inv = 1.0f / fmaxf(fabsf(den), em_t);
;       float ss = 0.f;
; #pragma unroll
;       for (int eb = 0; eb < 2; ++eb)
; #pragma unroll
;         for (int i = 0; i < 16; ++i) { const float hv = (num[eb][i] + si_t * G[eb][i]) * inv; num[eb][i] = hv; ss += hv * hv; }
;       ss += __shfl_xor(ss, 32);
;       const float rstd = rsqrtf(ss * (1.f / 64.f) + EPS_);
;       const bf16_t* bo = P + (tok0 + t) * PLD + C_BO + h * 64; bf16_t* yo = Y + (tok0 + t) * DM + 256 + h * 64;
; #pragma unroll
;       for (int eb = 0; eb < 2; ++eb)
; #pragma unroll
;         for (int g4 = 0; g4 < 4; ++g4) { const int e = 32 * eb + 8 * g4 + 4 * hi; const u32x2 bw = *(const u32x2*)(bo + e); const f32x4 gn = *(const f32x4*)(onorm + h * 64 + e);
;           const float o0 = num[eb][4 * g4] * rstd * gn.x * rcpf_(1.f + fexp(-bflo(bw.x))), o1 = num[eb][4 * g4 + 1] * rstd * gn.y * rcpf_(1.f + fexp(-bfhi(bw.x)));
	v_pk_add_f32 v[104:105], v[104:105], v[106:107]
	v_mov_b32_e32 v191, v33
	v_fmac_f32_e32 v105, v103, v104
	v_max_f32_e64 v102, |v105|, v102
	v_div_scale_f32 v104, s[2:3], v102, v102, 1.0
	v_rcp_f32_e32 v105, v104
	v_lshlrev_b32_e32 v178, 2, v128
	v_mov_b32_e32 v179, v33
	v_lshl_add_u64 v[178:179], v[100:101], 0, v[178:179]
	v_fma_f32 v106, -v104, v105, 1.0
	v_fmac_f32_e32 v105, v106, v105
	v_div_scale_f32 v106, vcc, 1.0, v102, 1.0
	v_mul_f32_e32 v107, v106, v105
	v_fma_f32 v108, -v104, v107, v106
	v_fmac_f32_e32 v107, v108, v105
	v_fma_f32 v104, -v104, v107, v106
	v_div_fmas_f32 v104, v104, v105, v107
	v_div_fixup_f32 v108, v104, v102, 1.0
	v_pk_mul_f32 v[102:103], v[10:11], v[108:109] op_sel_hi:[1,0]
	v_pk_fma_f32 v[10:11], v[210:211], v[12:13], v[28:29] op_sel_hi:[0,1,1]
	v_pk_mul_f32 v[26:27], v[10:11], v[108:109] op_sel_hi:[1,0]
	v_pk_fma_f32 v[10:11], v[210:211], v[14:15], v[30:31] op_sel_hi:[0,1,1]
	v_pk_mul_f32 v[28:29], v[10:11], v[108:109] op_sel_hi:[1,0]
	v_mad_u64_u32 v[10:11], s[2:3], v152, s82, v[154:155]
	v_mad_i32_i24 v11, v153, s82, v11
	v_lshl_add_u64 v[30:31], v[10:11], 0, v[32:33]
	v_lshl_add_u64 v[104:105], v[30:31], 0, v[174:175]
	global_load_dwordx2 v[176:177], v[104:105], off offset:3072
	v_lshlrev_b64 v[10:11], 11, v[152:153]
	v_lshl_add_u64 v[10:11], s[0:1], 0, v[10:11]
	v_lshl_add_u64 v[14:15], v[10:11], 0, v[32:33]
	v_lshlrev_b32_e32 v10, 2, v122
	v_mov_b32_e32 v11, v33
	v_lshl_add_u64 v[172:173], v[100:101], 0, v[10:11]
	global_load_dwordx4 v[10:13], v[172:173], off
	v_pk_mul_f32 v[106:107], v[102:103], v[102:103]
	v_pk_mul_f32 v[110:111], v[26:27], v[26:27]
	v_pk_mul_f32 v[206:207], v[28:29], v[28:29]
	v_lshl_add_u64 v[50:51], v[30:31], 0, v[182:183]
	v_lshl_add_u64 v[54:55], v[30:31], 0, v[190:191]
	v_lshlrev_b32_e32 v192, 1, v130
	v_mov_b32_e32 v193, v33
	v_lshl_add_u64 v[58:59], v[30:31], 0, v[192:193]
	v_lshlrev_b32_e32 v180, 2, v130
	v_mov_b32_e32 v181, v33
	v_lshl_add_u64 v[180:181], v[100:101], 0, v[180:181]
	v_lshlrev_b32_e32 v204, 1, v136
	v_mov_b32_e32 v205, v33
	v_lshl_add_u64 v[16:17], v[30:31], 0, v[204:205]
	v_lshlrev_b32_e32 v184, 2, v136
	v_mov_b32_e32 v185, v33
	v_lshl_add_u64 v[186:187], v[100:101], 0, v[184:185]
	v_lshlrev_b32_e32 v184, 1, v138
	v_lshl_add_u64 v[20:21], v[30:31], 0, v[184:185]
	v_lshlrev_b32_e32 v188, 2, v138
	v_mov_b32_e32 v189, v33
	v_lshl_add_u64 v[188:189], v[100:101], 0, v[188:189]
	s_waitcnt vmcnt(1)
	v_lshlrev_b32_e32 v109, 16, v176
	v_mul_f32_e32 v109, 0xbfb8aa3b, v109
	v_exp_f32_e32 v109, v109
	s_nop 0
	v_add_f32_e32 v109, 1.0, v109
	v_rcp_f32_e32 v112, v109
	v_and_b32_e32 v109, 0xffff0000, v176
	v_mul_f32_e32 v109, 0xbfb8aa3b, v109
	v_exp_f32_e32 v109, v109
	v_lshlrev_b32_e32 v176, 2, v126
	v_add_f32_e32 v109, 1.0, v109
	v_rcp_f32_e32 v113, v109
	v_lshlrev_b32_e32 v109, 16, v177
	v_mul_f32_e32 v109, 0xbfb8aa3b, v109
	v_exp_f32_e32 v109, v109
	s_nop 0
	v_add_f32_e32 v109, 1.0, v109
	v_rcp_f32_e32 v208, v109
	v_and_b32_e32 v109, 0xffff0000, v177
	v_mul_f32_e32 v109, 0xbfb8aa3b, v109
	v_exp_f32_e32 v109, v109
	v_mov_b32_e32 v177, v33
	v_lshl_add_u64 v[176:177], v[100:101], 0, v[176:177]
	v_add_f32_e32 v109, 1.0, v109
	v_pk_mul_f32 v[52:53], v[34:35], v[108:109] op_sel_hi:[1,0]
	v_pk_mul_f32 v[36:37], v[36:37], v[108:109] op_sel_hi:[1,0]
	v_pk_mul_f32 v[214:215], v[52:53], v[52:53]
	v_pk_mul_f32 v[212:213], v[36:37], v[36:37]
	v_pk_mul_f32 v[40:41], v[40:41], v[108:109] op_sel_hi:[1,0]
	v_pk_mul_f32 v[56:57], v[38:39], v[108:109] op_sel_hi:[1,0]
	v_pk_mul_f32 v[44:45], v[44:45], v[108:109] op_sel_hi:[1,0]
	v_pk_mul_f32 v[60:61], v[42:43], v[108:109] op_sel_hi:[1,0]
	v_pk_mul_f32 v[48:49], v[48:49], v[108:109] op_sel_hi:[1,0]
	v_pk_mul_f32 v[62:63], v[46:47], v[108:109] op_sel_hi:[1,0]
	v_pk_mul_f32 v[2:3], v[2:3], v[108:109] op_sel_hi:[1,0]
	v_pk_mul_f32 v[18:19], v[0:1], v[108:109] op_sel_hi:[1,0]
	v_pk_mul_f32 v[6:7], v[6:7], v[108:109] op_sel_hi:[1,0]
	v_pk_mul_f32 v[22:23], v[4:5], v[108:109] op_sel_hi:[1,0]
	v_pk_mul_f32 v[8:9], v[8:9], v[108:109] op_sel_hi:[1,0]
	v_add_f32_e32 v108, v214, v215
	v_add_f32_e32 v108, v212, v108
	v_pk_mul_f32 v[218:219], v[56:57], v[56:57]
	v_add_f32_e32 v108, v213, v108
	v_add_f32_e32 v108, v218, v108
	v_pk_mul_f32 v[216:217], v[40:41], v[40:41]
	v_add_f32_e32 v108, v219, v108
	v_add_f32_e32 v108, v216, v108
	v_pk_mul_f32 v[222:223], v[60:61], v[60:61]
	v_add_f32_e32 v108, v217, v108
	v_add_f32_e32 v108, v222, v108
	v_pk_mul_f32 v[220:221], v[44:45], v[44:45]
	v_add_f32_e32 v108, v223, v108
	v_add_f32_e32 v108, v220, v108
	v_pk_mul_f32 v[224:225], v[62:63], v[62:63]
	v_add_f32_e32 v108, v221, v108
	v_add_f32_e32 v108, v224, v108
	v_pk_mul_f32 v[64:65], v[48:49], v[48:49]
	v_add_f32_e32 v108, v225, v108
	v_add_f32_e32 v64, v64, v108
	v_pk_mul_f32 v[0:1], v[18:19], v[18:19]
	v_add_f32_e32 v64, v65, v64
	v_add_f32_e32 v0, v0, v64
	v_pk_mul_f32 v[226:227], v[2:3], v[2:3]
	v_add_f32_e32 v0, v1, v0
	v_add_f32_e32 v0, v226, v0
	v_pk_mul_f32 v[230:231], v[22:23], v[22:23]
	v_add_f32_e32 v0, v227, v0
	v_add_f32_e32 v0, v230, v0
	v_pk_mul_f32 v[228:229], v[6:7], v[6:7]
	v_add_f32_e32 v0, v231, v0
	v_add_f32_e32 v0, v228, v0
	v_pk_mul_f32 v[24:25], v[8:9], v[8:9]
	v_add_f32_e32 v0, v229, v0
	v_add_f32_e32 v0, v24, v0
	v_add_f32_e32 v0, v25, v0
	v_add_f32_e32 v0, v106, v0
	v_add_f32_e32 v0, v107, v0
	v_add_f32_e32 v0, v110, v0
	v_add_f32_e32 v0, v111, v0
	v_add_f32_e32 v0, v206, v0
	v_add_f32_e32 v0, v207, v0
	ds_bpermute_b32 v1, v141, v0
	v_rcp_f32_e32 v209, v109
	v_lshl_add_u64 v[34:35], v[14:15], 0, v[174:175]
	v_lshl_add_u64 v[38:39], v[14:15], 0, v[182:183]
	v_lshl_add_u64 v[42:43], v[14:15], 0, v[190:191]
	s_waitcnt lgkmcnt(0)
; DI unsigned pk2(float a, float b) { return pg8::cvt_pk_bf16(a, b); }
; DI float bflo(unsigned w) { return __uint_as_float(w << 16); }
; DI float bfhi(unsigned w) { return __uint_as_float(w & 0xffff0000u); }
; DI float rcpf_(float x) { return __builtin_amdgcn_rcpf(x); }
; DI float fexp(float x) { return ex2(x * LOG2E); }
; DI void b3_phase(const bf16_t* P, const bf16_t* BQ, const bf16_t* BK, const bf16_t* VtB, const float* DC, const float* SC, const float* gate_bias, const float* onorm, bf16_t* Y, unsigned char* lds, int tid) {
;     ...
;       ss += __shfl_xor(ss, 32);
;       const float rstd = rsqrtf(ss * (1.f / 64.f) + EPS_);
;       const bf16_t* bo = P + (tok0 + t) * PLD + C_BO + h * 64; bf16_t* yo = Y + (tok0 + t) * DM + 256 + h * 64;
; #pragma unroll
;       for (int eb = 0; eb < 2; ++eb)
; #pragma unroll
;         for (int g4 = 0; g4 < 4; ++g4) { const int e = 32 * eb + 8 * g4 + 4 * hi; const u32x2 bw = *(const u32x2*)(bo + e); const f32x4 gn = *(const f32x4*)(onorm + h * 64 + e);
;           const float o0 = num[eb][4 * g4] * rstd * gn.x * rcpf_(1.f + fexp(-bflo(bw.x))), o1 = num[eb][4 * g4 + 1] * rstd * gn.y * rcpf_(1.f + fexp(-bfhi(bw.x)));
;           const float o2 = num[eb][4 * g4 + 2] * rstd * gn.z * rcpf_(1.f + fexp(-bflo(bw.y))), o3 = num[eb][4 * g4 + 3] * rstd * gn.w * rcpf_(1.f + fexp(-bfhi(bw.y)));
;           u32x2 ow; ow.x = pk2(o0, o1); ow.y = pk2(o2, o3); *(u32x2*)(yo + e) = ow; }
	v_add_f32_e32 v0, v0, v1
	v_fmamk_f32 v0, v0, 0x3c800000, v237
	v_cmp_gt_f32_e32 vcc, s97, v0
	v_mul_f32_e32 v1, 0x4b800000, v0
	v_lshl_add_u64 v[46:47], v[14:15], 0, v[192:193]
	v_cndmask_b32_e32 v0, v0, v1, vcc
	v_rsq_f32_e32 v0, v0
	v_lshl_add_u64 v[4:5], v[14:15], 0, v[204:205]
	v_lshlrev_b32_e32 v206, 1, v140
	v_mov_b32_e32 v207, v33
	v_mul_f32_e32 v1, 0x45800000, v0
	v_cndmask_b32_e32 v0, v0, v1, vcc
	v_pk_mul_f32 v[24:25], v[52:53], v[0:1] op_sel_hi:[1,0]
	s_waitcnt vmcnt(0)
	v_pk_mul_f32 v[10:11], v[10:11], v[24:25]
	v_pk_mul_f32 v[24:25], v[36:37], v[0:1] op_sel_hi:[1,0]
	v_pk_mul_f32 v[10:11], v[112:113], v[10:11]
	v_pk_mul_f32 v[12:13], v[12:13], v[24:25]
	v_cvt_pk_bf16_f32 v10, v10, v11
	v_pk_mul_f32 v[12:13], v[208:209], v[12:13]
	s_nop 0
	v_cvt_pk_bf16_f32 v11, v12, v13
	global_store_dwordx2 v[34:35], v[10:11], off offset:512
	global_load_dwordx2 v[24:25], v[50:51], off offset:3072
	s_nop 0
	global_load_dwordx4 v[10:13], v[176:177], off
	s_waitcnt vmcnt(1)
	v_lshlrev_b32_e32 v1, 16, v24
	v_mul_f32_e32 v1, 0xbfb8aa3b, v1
	v_exp_f32_e32 v1, v1
	s_nop 0
	v_add_f32_e32 v1, 1.0, v1
	v_rcp_f32_e32 v36, v1
	v_pk_mul_f32 v[50:51], v[56:57], v[0:1] op_sel_hi:[1,0]
	v_and_b32_e32 v1, 0xffff0000, v24
	v_mul_f32_e32 v1, 0xbfb8aa3b, v1
	v_exp_f32_e32 v1, v1
	s_waitcnt vmcnt(0)
	v_pk_mul_f32 v[10:11], v[10:11], v[50:51]
	v_add_f32_e32 v1, 1.0, v1
	v_rcp_f32_e32 v37, v1
	v_lshlrev_b32_e32 v1, 16, v25
	v_mul_f32_e32 v1, 0xbfb8aa3b, v1
	v_exp_f32_e32 v1, v1
	v_pk_mul_f32 v[10:11], v[36:37], v[10:11]
	v_add_f32_e32 v1, 1.0, v1
	v_rcp_f32_e32 v24, v1
	v_pk_mul_f32 v[36:37], v[40:41], v[0:1] op_sel_hi:[1,0]
	v_and_b32_e32 v1, 0xffff0000, v25
	v_mul_f32_e32 v1, 0xbfb8aa3b, v1
	v_exp_f32_e32 v1, v1
	v_pk_mul_f32 v[12:13], v[12:13], v[36:37]
	v_cvt_pk_bf16_f32 v10, v10, v11
	v_add_f32_e32 v1, 1.0, v1
	v_rcp_f32_e32 v25, v1
	s_nop 0
	v_pk_mul_f32 v[12:13], v[24:25], v[12:13]
	s_nop 0
	v_cvt_pk_bf16_f32 v11, v12, v13
	global_store_dwordx2 v[38:39], v[10:11], off offset:512
	global_load_dwordx2 v[24:25], v[54:55], off offset:3072
	s_nop 0
	global_load_dwordx4 v[10:13], v[178:179], off
	s_waitcnt vmcnt(1)
	v_lshlrev_b32_e32 v1, 16, v24
	v_mul_f32_e32 v1, 0xbfb8aa3b, v1
	v_exp_f32_e32 v1, v1
	s_nop 0
	v_add_f32_e32 v1, 1.0, v1
	v_rcp_f32_e32 v36, v1
	v_pk_mul_f32 v[38:39], v[60:61], v[0:1] op_sel_hi:[1,0]
	v_and_b32_e32 v1, 0xffff0000, v24
	v_mul_f32_e32 v1, 0xbfb8aa3b, v1
	v_exp_f32_e32 v1, v1
	s_waitcnt vmcnt(0)
	v_pk_mul_f32 v[10:11], v[10:11], v[38:39]
	v_add_f32_e32 v1, 1.0, v1
	v_rcp_f32_e32 v37, v1
	v_lshlrev_b32_e32 v1, 16, v25
	v_mul_f32_e32 v1, 0xbfb8aa3b, v1
	v_exp_f32_e32 v1, v1
	v_pk_mul_f32 v[10:11], v[36:37], v[10:11]
	v_add_f32_e32 v1, 1.0, v1
	v_rcp_f32_e32 v24, v1
	v_pk_mul_f32 v[36:37], v[44:45], v[0:1] op_sel_hi:[1,0]
	v_and_b32_e32 v1, 0xffff0000, v25
	v_mul_f32_e32 v1, 0xbfb8aa3b, v1
	v_exp_f32_e32 v1, v1
	v_pk_mul_f32 v[12:13], v[12:13], v[36:37]
	v_cvt_pk_bf16_f32 v10, v10, v11
	v_add_f32_e32 v1, 1.0, v1
	v_rcp_f32_e32 v25, v1
	s_nop 0
	v_pk_mul_f32 v[12:13], v[24:25], v[12:13]
	s_nop 0
	v_cvt_pk_bf16_f32 v11, v12, v13
	global_store_dwordx2 v[42:43], v[10:11], off offset:512
	global_load_dwordx2 v[24:25], v[58:59], off offset:3072
	s_nop 0
	global_load_dwordx4 v[10:13], v[180:181], off
	s_waitcnt vmcnt(1)
	v_lshlrev_b32_e32 v1, 16, v24
	v_mul_f32_e32 v1, 0xbfb8aa3b, v1
	v_exp_f32_e32 v1, v1
	s_nop 0
	v_add_f32_e32 v1, 1.0, v1
	v_rcp_f32_e32 v36, v1
	v_pk_mul_f32 v[38:39], v[62:63], v[0:1] op_sel_hi:[1,0]
	v_and_b32_e32 v1, 0xffff0000, v24
	v_mul_f32_e32 v1, 0xbfb8aa3b, v1
	v_exp_f32_e32 v1, v1
	s_waitcnt vmcnt(0)
	v_pk_mul_f32 v[10:11], v[10:11], v[38:39]
	v_add_f32_e32 v1, 1.0, v1
	v_rcp_f32_e32 v37, v1
	v_lshlrev_b32_e32 v1, 16, v25
	v_mul_f32_e32 v1, 0xbfb8aa3b, v1
	v_exp_f32_e32 v1, v1
	v_pk_mul_f32 v[10:11], v[36:37], v[10:11]
	v_add_f32_e32 v1, 1.0, v1
	v_rcp_f32_e32 v24, v1
	v_pk_mul_f32 v[36:37], v[48:49], v[0:1] op_sel_hi:[1,0]
	v_and_b32_e32 v1, 0xffff0000, v25
	v_mul_f32_e32 v1, 0xbfb8aa3b, v1
	v_exp_f32_e32 v1, v1
	v_pk_mul_f32 v[12:13], v[12:13], v[36:37]
	v_cvt_pk_bf16_f32 v10, v10, v11
	v_add_f32_e32 v1, 1.0, v1
	v_rcp_f32_e32 v25, v1
	s_nop 0
	v_pk_mul_f32 v[12:13], v[24:25], v[12:13]
	s_nop 0
	v_cvt_pk_bf16_f32 v11, v12, v13
	global_store_dwordx2 v[46:47], v[10:11], off offset:512
	global_load_dwordx2 v[24:25], v[104:105], off offset:3136
	s_nop 0
	global_load_dwordx4 v[10:13], v[172:173], off offset:128
	s_waitcnt vmcnt(1)
	v_lshlrev_b32_e32 v1, 16, v24
	v_mul_f32_e32 v1, 0xbfb8aa3b, v1
	v_exp_f32_e32 v1, v1
	s_nop 0
	v_add_f32_e32 v1, 1.0, v1
	v_rcp_f32_e32 v36, v1
	v_pk_mul_f32 v[18:19], v[18:19], v[0:1] op_sel_hi:[1,0]
	v_and_b32_e32 v1, 0xffff0000, v24
	v_mul_f32_e32 v1, 0xbfb8aa3b, v1
	v_exp_f32_e32 v1, v1
	s_waitcnt vmcnt(0)
	v_pk_mul_f32 v[10:11], v[10:11], v[18:19]
	v_add_f32_e32 v1, 1.0, v1
	v_rcp_f32_e32 v37, v1
	v_lshlrev_b32_e32 v1, 16, v25
	v_mul_f32_e32 v1, 0xbfb8aa3b, v1
	v_exp_f32_e32 v1, v1
	v_pk_mul_f32 v[10:11], v[36:37], v[10:11]
	v_add_f32_e32 v1, 1.0, v1
	v_rcp_f32_e32 v18, v1
	v_pk_mul_f32 v[2:3], v[2:3], v[0:1] op_sel_hi:[1,0]
	v_and_b32_e32 v1, 0xffff0000, v25
	v_mul_f32_e32 v1, 0xbfb8aa3b, v1
	v_exp_f32_e32 v1, v1
	v_pk_mul_f32 v[2:3], v[12:13], v[2:3]
	v_cvt_pk_bf16_f32 v10, v10, v11
	v_add_f32_e32 v1, 1.0, v1
	v_rcp_f32_e32 v19, v1
	s_nop 0
	v_pk_mul_f32 v[2:3], v[18:19], v[2:3]
	s_nop 0
	v_cvt_pk_bf16_f32 v11, v2, v3
	global_store_dwordx2 v[34:35], v[10:11], off offset:576
	global_load_dwordx2 v[2:3], v[16:17], off offset:3072
	s_nop 0
	global_load_dwordx4 v[10:13], v[186:187], off
	s_waitcnt vmcnt(1)
; DI unsigned pk2(float a, float b) { return pg8::cvt_pk_bf16(a, b); }
; DI float bflo(unsigned w) { return __uint_as_float(w << 16); }
; DI float bfhi(unsigned w) { return __uint_as_float(w & 0xffff0000u); }
; DI float rcpf_(float x) { return __builtin_amdgcn_rcpf(x); }
; #define MFMA32(a, b, c) __builtin_amdgcn_mfma_f32_32x32x16_bf16((a), (b), (c), 0, 0, 0)
; DI float fexp(float x) { return ex2(x * LOG2E); }
; DI void b3_phase(const bf16_t* P, const bf16_t* BQ, const bf16_t* BK, const bf16_t* VtB, const float* DC, const float* SC, const float* gate_bias, const float* onorm, bf16_t* Y, unsigned char* lds, int tid) {
;     ...
;     for (int tq = 0; tq < 2; ++tq) {
;       const int t = 32 * tq + r32; const float mu_t = MU[t], si_t = SI[t], em_t = EM[t];
;       bf16x8 qf[4]; float qn = 0.f;
; #pragma unroll
;       for (int ks = 0; ks < 4; ++ks) {
;         const u32x4 qw = *(const u32x4*)(BQ + (tok0 + t) * 256 + h * 64 + 16 * ks + 8 * hi); qf[ks] = __builtin_bit_cast(bf16x8, qw);
;         const f32x4 na = *(const f32x4*)(NV + 16 * ks + 8 * hi), nb = *(const f32x4*)(NV + 16 * ks + 8 * hi + 4);
;         qn += bflo(qw.x) * na.x + bfhi(qw.x) * na.y + bflo(qw.y) * na.z + bfhi(qw.y) * na.w + bflo(qw.z) * nb.x + bfhi(qw.z) * nb.y + bflo(qw.w) * nb.z + bfhi(qw.w) * nb.w;
;       }
;       qn += __shfl_xor(qn, 32);
;       f32x16 G[2], num[2];
; #pragma unroll
;       for (int eb = 0; eb < 2; ++eb) { G[eb] = splat16(0.f); num[eb] = splat16(0.f);
; #pragma unroll
;         for (int ks = 0; ks < 4; ++ks) G[eb] = MFMA32(cfr[eb][ks], qf[ks], G[eb]); }
;     ...
;       for (int eb = 0; eb < 2; ++eb)
; #pragma unroll
;         for (int g4 = 0; g4 < 4; ++g4) { const int e = 32 * eb + 8 * g4 + 4 * hi; const u32x2 bw = *(const u32x2*)(bo + e); const f32x4 gn = *(const f32x4*)(onorm + h * 64 + e);
;           const float o0 = num[eb][4 * g4] * rstd * gn.x * rcpf_(1.f + fexp(-bflo(bw.x))), o1 = num[eb][4 * g4 + 1] * rstd * gn.y * rcpf_(1.f + fexp(-bfhi(bw.x)));
;           const float o2 = num[eb][4 * g4 + 2] * rstd * gn.z * rcpf_(1.f + fexp(-bflo(bw.y))), o3 = num[eb][4 * g4 + 3] * rstd * gn.w * rcpf_(1.f + fexp(-bfhi(bw.y)));
;           u32x2 ow; ow.x = pk2(o0, o1); ow.y = pk2(o2, o3); *(u32x2*)(yo + e) = ow; }
	v_lshlrev_b32_e32 v1, 16, v2
	v_mul_f32_e32 v1, 0xbfb8aa3b, v1
	v_exp_f32_e32 v1, v1
	s_nop 0
	v_add_f32_e32 v1, 1.0, v1
	v_rcp_f32_e32 v16, v1
	v_pk_mul_f32 v[18:19], v[22:23], v[0:1] op_sel_hi:[1,0]
	v_and_b32_e32 v1, 0xffff0000, v2
	v_mul_f32_e32 v1, 0xbfb8aa3b, v1
	v_exp_f32_e32 v1, v1
	s_waitcnt vmcnt(0)
	v_pk_mul_f32 v[10:11], v[10:11], v[18:19]
	v_add_f32_e32 v1, 1.0, v1
	v_rcp_f32_e32 v17, v1
	v_lshlrev_b32_e32 v1, 16, v3
	v_mul_f32_e32 v1, 0xbfb8aa3b, v1
	v_exp_f32_e32 v1, v1
	v_pk_mul_f32 v[10:11], v[16:17], v[10:11]
	v_add_f32_e32 v1, 1.0, v1
	v_rcp_f32_e32 v2, v1
	v_pk_mul_f32 v[6:7], v[6:7], v[0:1] op_sel_hi:[1,0]
	v_and_b32_e32 v1, 0xffff0000, v3
	v_mul_f32_e32 v1, 0xbfb8aa3b, v1
	v_exp_f32_e32 v1, v1
	v_pk_mul_f32 v[6:7], v[12:13], v[6:7]
	v_add_f32_e32 v1, 1.0, v1
	v_rcp_f32_e32 v3, v1
	s_nop 0
	v_pk_mul_f32 v[2:3], v[2:3], v[6:7]
	v_cvt_pk_bf16_f32 v6, v10, v11
	v_cvt_pk_bf16_f32 v7, v2, v3
	global_store_dwordx2 v[4:5], v[6:7], off offset:512
	global_load_dwordx2 v[6:7], v[20:21], off offset:3072
	s_nop 0
	global_load_dwordx4 v[2:5], v[188:189], off
	s_waitcnt vmcnt(1)
	v_lshlrev_b32_e32 v1, 16, v6
	v_mul_f32_e32 v1, 0xbfb8aa3b, v1
	v_exp_f32_e32 v1, v1
	s_nop 0
	v_add_f32_e32 v1, 1.0, v1
	v_rcp_f32_e32 v10, v1
	v_pk_mul_f32 v[8:9], v[8:9], v[0:1] op_sel_hi:[1,0]
	v_and_b32_e32 v1, 0xffff0000, v6
	v_mul_f32_e32 v1, 0xbfb8aa3b, v1
	v_exp_f32_e32 v1, v1
	s_waitcnt vmcnt(0)
	v_pk_mul_f32 v[2:3], v[2:3], v[8:9]
	v_add_f32_e32 v1, 1.0, v1
	v_rcp_f32_e32 v11, v1
	v_lshlrev_b32_e32 v1, 16, v7
	v_mul_f32_e32 v1, 0xbfb8aa3b, v1
	v_exp_f32_e32 v1, v1
	v_pk_mul_f32 v[2:3], v[10:11], v[2:3]
	v_add_f32_e32 v1, 1.0, v1
	v_rcp_f32_e32 v6, v1
	v_and_b32_e32 v1, 0xffff0000, v7
	v_mul_f32_e32 v1, 0xbfb8aa3b, v1
	v_exp_f32_e32 v1, v1
	v_cvt_pk_bf16_f32 v2, v2, v3
	v_add_f32_e32 v1, 1.0, v1
	v_rcp_f32_e32 v7, v1
	v_pk_mul_f32 v[8:9], v[102:103], v[0:1] op_sel_hi:[1,0]
	s_nop 0
	v_pk_mul_f32 v[4:5], v[4:5], v[8:9]
	s_nop 0
	v_pk_mul_f32 v[4:5], v[6:7], v[4:5]
	s_nop 0
	v_cvt_pk_bf16_f32 v3, v4, v5
	v_lshl_add_u64 v[4:5], v[14:15], 0, v[184:185]
	global_store_dwordx2 v[4:5], v[2:3], off offset:512
	v_lshl_add_u64 v[2:3], v[30:31], 0, v[206:207]
	global_load_dwordx2 v[6:7], v[2:3], off offset:3072
	v_lshlrev_b32_e32 v2, 2, v140
	v_mov_b32_e32 v3, v33
	v_lshl_add_u64 v[208:209], v[100:101], 0, v[2:3]
	global_load_dwordx4 v[2:5], v[208:209], off
	s_waitcnt vmcnt(1)
	v_lshlrev_b32_e32 v1, 16, v6
	v_mul_f32_e32 v1, 0xbfb8aa3b, v1
	v_exp_f32_e32 v1, v1
	s_nop 0
	v_add_f32_e32 v1, 1.0, v1
	v_rcp_f32_e32 v8, v1
	v_and_b32_e32 v1, 0xffff0000, v6
	v_mul_f32_e32 v1, 0xbfb8aa3b, v1
	v_exp_f32_e32 v1, v1
	s_nop 0
	v_add_f32_e32 v1, 1.0, v1
	v_rcp_f32_e32 v9, v1
	v_pk_mul_f32 v[10:11], v[26:27], v[0:1] op_sel_hi:[1,0]
	v_lshlrev_b32_e32 v1, 16, v7
	v_mul_f32_e32 v1, 0xbfb8aa3b, v1
	v_exp_f32_e32 v1, v1
	s_waitcnt vmcnt(0)
	v_pk_mul_f32 v[2:3], v[2:3], v[10:11]
	v_add_f32_e32 v1, 1.0, v1
	v_rcp_f32_e32 v6, v1
	v_and_b32_e32 v1, 0xffff0000, v7
	v_mul_f32_e32 v1, 0xbfb8aa3b, v1
	v_exp_f32_e32 v1, v1
	v_pk_mul_f32 v[2:3], v[8:9], v[2:3]
	v_add_f32_e32 v1, 1.0, v1
	v_rcp_f32_e32 v7, v1
	v_pk_mul_f32 v[0:1], v[28:29], v[0:1] op_sel_hi:[1,0]
	v_cvt_pk_bf16_f32 v2, v2, v3
	v_pk_mul_f32 v[0:1], v[4:5], v[0:1]
	s_nop 0
	v_pk_mul_f32 v[0:1], v[6:7], v[0:1]
	s_nop 0
	v_cvt_pk_bf16_f32 v3, v0, v1
	v_lshl_add_u64 v[0:1], v[14:15], 0, v[206:207]
	global_store_dwordx2 v[0:1], v[2:3], off offset:512
	v_lshl_add_u64 v[0:1], v[98:99], 0, v[164:165]
	ds_read2_b32 v[210:211], v147 offset0:96 offset1:160
	ds_read_b32 v149, v147 offset:896
	global_load_dwordx4 v[98:101], v[0:1], off
	ds_read_b128 v[2:5], v139 offset:1024
	ds_read_b128 v[6:9], v139 offset:1040
	global_load_dwordx4 v[110:113], v[0:1], off offset:32
	s_waitcnt vmcnt(1)
	v_mfma_f32_32x32x16_bf16 v[16:31], v[66:69], v[98:101], 0
	v_lshlrev_b32_e32 v10, 16, v98
	s_waitcnt lgkmcnt(1)
	v_mul_f32_e32 v212, v2, v10
	v_and_b32_e32 v2, 0xffff0000, v98
	v_mul_f32_e32 v226, v3, v2
	v_lshlrev_b32_e32 v2, 16, v99
	v_mul_f32_e32 v224, v4, v2
	v_and_b32_e32 v2, 0xffff0000, v99
	v_mul_f32_e32 v222, v5, v2
	v_lshlrev_b32_e32 v2, 16, v100
	s_waitcnt lgkmcnt(0)
	v_mul_f32_e32 v220, v6, v2
	v_and_b32_e32 v2, 0xffff0000, v100
	v_mul_f32_e32 v218, v7, v2
	v_lshlrev_b32_e32 v2, 16, v101
	v_mul_f32_e32 v216, v8, v2
	v_and_b32_e32 v2, 0xffff0000, v101
	v_mul_f32_e32 v214, v9, v2
	ds_read_b128 v[2:5], v139 offset:1088
	ds_read_b128 v[6:9], v139 offset:1104
	global_load_dwordx4 v[106:109], v[0:1], off offset:64
	s_waitcnt vmcnt(1)
	v_and_b32_e32 v11, 0xffff0000, v110
	v_lshlrev_b32_e32 v10, 16, v110
	s_waitcnt lgkmcnt(1)
	v_mul_f32_e32 v12, v3, v11
	v_pk_fma_f32 v[2:3], v[2:3], v[10:11], v[12:13] op_sel_hi:[1,1,0]
	v_and_b32_e32 v11, 0xffff0000, v111
	v_lshlrev_b32_e32 v10, 16, v111
	v_pk_fma_f32 v[2:3], v[4:5], v[10:11], v[2:3]
	v_mul_f32_e32 v4, v5, v11
	v_pk_add_f32 v[2:3], v[4:5], v[2:3] op_sel_hi:[0,1]
	v_and_b32_e32 v5, 0xffff0000, v112
	v_lshlrev_b32_e32 v4, 16, v112
	s_waitcnt lgkmcnt(0)
	v_pk_fma_f32 v[2:3], v[6:7], v[4:5], v[2:3]
	v_mul_f32_e32 v4, v7, v5
	v_pk_add_f32 v[2:3], v[4:5], v[2:3] op_sel_hi:[0,1]
	v_and_b32_e32 v5, 0xffff0000, v113
	v_lshlrev_b32_e32 v4, 16, v113
	v_pk_fma_f32 v[2:3], v[8:9], v[4:5], v[2:3]
	v_mul_f32_e32 v4, v9, v5
	v_pk_add_f32 v[228:229], v[4:5], v[2:3] op_sel_hi:[0,1]
	ds_read_b128 v[2:5], v139 offset:1152
	ds_read_b128 v[6:9], v139 offset:1168
	global_load_dwordx4 v[102:105], v[0:1], off offset:96
	v_mfma_f32_32x32x16_bf16 v[16:31], v[70:73], v[110:113], v[16:31]
	s_waitcnt vmcnt(1)
	v_and_b32_e32 v11, 0xffff0000, v106
	v_lshlrev_b32_e32 v10, 16, v106
	s_waitcnt lgkmcnt(1)
; DI float bflo(unsigned w) { return __uint_as_float(w << 16); }
; DI float bfhi(unsigned w) { return __uint_as_float(w & 0xffff0000u); }
; #define MFMA32(a, b, c) __builtin_amdgcn_mfma_f32_32x32x16_bf16((a), (b), (c), 0, 0, 0)
; DI float fexp(float x) { return ex2(x * LOG2E); }
; DI void b3_phase(const bf16_t* P, const bf16_t* BQ, const bf16_t* BK, const bf16_t* VtB, const float* DC, const float* SC, const float* gate_bias, const float* onorm, bf16_t* Y, unsigned char* lds, int tid) {
;     ...
;     for (int tq = 0; tq < 2; ++tq) {
;       const int t = 32 * tq + r32; const float mu_t = MU[t], si_t = SI[t], em_t = EM[t];
;       bf16x8 qf[4]; float qn = 0.f;
; #pragma unroll
;       for (int ks = 0; ks < 4; ++ks) {
;         const u32x4 qw = *(const u32x4*)(BQ + (tok0 + t) * 256 + h * 64 + 16 * ks + 8 * hi); qf[ks] = __builtin_bit_cast(bf16x8, qw);
;         const f32x4 na = *(const f32x4*)(NV + 16 * ks + 8 * hi), nb = *(const f32x4*)(NV + 16 * ks + 8 * hi + 4);
;         qn += bflo(qw.x) * na.x + bfhi(qw.x) * na.y + bflo(qw.y) * na.z + bfhi(qw.y) * na.w + bflo(qw.z) * nb.x + bfhi(qw.z) * nb.y + bflo(qw.w) * nb.z + bfhi(qw.w) * nb.w;
;       }
;       qn += __shfl_xor(qn, 32);
;       f32x16 G[2], num[2];
; #pragma unroll
;       for (int eb = 0; eb < 2; ++eb) { G[eb] = splat16(0.f); num[eb] = splat16(0.f);
; #pragma unroll
;         for (int ks = 0; ks < 4; ++ks) G[eb] = MFMA32(cfr[eb][ks], qf[ks], G[eb]); }
;       float dsum = 0.f;
; #pragma unroll
;       for (int tk = 0; tk < 2; ++tk) {
;         if (tk <= tq) {
;           f32x16 S = splat16(0.f);
; #pragma unroll
;           for (int ks = 0; ks < 4; ++ks) { const bf16x8 kf = *(const bf16x8*)(BK + (tok0 + 32 * tk + r32) * 256 + h * 64 + 16 * ks + 8 * hi); S = MFMA32(kf, qf[ks], S); }
;           asm volatile("" ::: "memory");
; #pragma unroll
;           for (int g4 = 0; g4 < 4; ++g4) { const f32x4 rv = *(const f32x4*)(R + 32 * tk + 8 * g4 + 4 * hi);
; #pragma unroll
;             for (int j = 0; j < 4; ++j) { const int s = 32 * tk + 8 * g4 + 4 * hi + j; const float w = (s <= t) ? fexp(rv[j] - mu_t) : 0.f; const float val = S[4 * g4 + j] * w; dsum += val; S[4 * g4 + j] = val; } }
; #pragma unroll
;           for (int kk = 0; kk < 2; ++kk) { const bf16x8 pf = pack8(S, kk);
	v_mul_f32_e32 v12, v3, v11
	v_pk_fma_f32 v[2:3], v[2:3], v[10:11], v[12:13] op_sel_hi:[1,1,0]
	v_and_b32_e32 v11, 0xffff0000, v107
	v_lshlrev_b32_e32 v10, 16, v107
	v_pk_fma_f32 v[2:3], v[4:5], v[10:11], v[2:3]
	v_mul_f32_e32 v4, v5, v11
	v_pk_add_f32 v[2:3], v[4:5], v[2:3] op_sel_hi:[0,1]
	v_and_b32_e32 v5, 0xffff0000, v108
	v_lshlrev_b32_e32 v4, 16, v108
	s_waitcnt lgkmcnt(0)
	v_pk_fma_f32 v[2:3], v[6:7], v[4:5], v[2:3]
	v_mul_f32_e32 v4, v7, v5
	v_pk_add_f32 v[2:3], v[4:5], v[2:3] op_sel_hi:[0,1]
	v_and_b32_e32 v5, 0xffff0000, v109
	v_lshlrev_b32_e32 v4, 16, v109
	v_pk_fma_f32 v[2:3], v[8:9], v[4:5], v[2:3]
	v_mul_f32_e32 v4, v9, v5
	v_pk_add_f32 v[230:231], v[4:5], v[2:3] op_sel_hi:[0,1]
	ds_read_b128 v[0:3], v139 offset:1216
	ds_read_b128 v[4:7], v139 offset:1232
	global_load_dwordx4 v[34:37], v[170:171], off
	global_load_dwordx4 v[50:53], v[170:171], off offset:32
	s_waitcnt vmcnt(1)
	v_mfma_f32_32x32x16_bf16 v[34:49], v[34:37], v[98:101], 0
	v_and_b32_e32 v9, 0xffff0000, v102
	v_lshlrev_b32_e32 v8, 16, v102
	s_waitcnt lgkmcnt(1)
	v_mul_f32_e32 v10, v1, v9
	v_fma_f32 v0, v0, v8, v10
	v_fma_f32 v1, v1, v9, v10
	v_and_b32_e32 v9, 0xffff0000, v103
	v_lshlrev_b32_e32 v8, 16, v103
	v_pk_fma_f32 v[0:1], v[2:3], v[8:9], v[0:1]
	s_waitcnt vmcnt(0)
	v_mfma_f32_32x32x16_bf16 v[34:49], v[50:53], v[110:113], v[34:49]
	global_load_dwordx4 v[50:53], v[170:171], off offset:64
	v_mul_f32_e32 v2, v3, v9
	v_add_f32_e64 v0, v2, v0
	v_add_f32_e64 v1, v2, v1
	v_and_b32_e32 v3, 0xffff0000, v104
	v_lshlrev_b32_e32 v2, 16, v104
	s_waitcnt lgkmcnt(0)
	v_pk_fma_f32 v[0:1], v[4:5], v[2:3], v[0:1]
	v_mul_f32_e32 v2, v5, v3
	s_waitcnt vmcnt(0)
	v_mfma_f32_32x32x16_bf16 v[34:49], v[50:53], v[106:109], v[34:49]
	global_load_dwordx4 v[50:53], v[170:171], off offset:96
	v_add_f32_e64 v0, v2, v0
	v_add_f32_e64 v1, v2, v1
	v_and_b32_e32 v3, 0xffff0000, v105
	v_lshlrev_b32_e32 v2, 16, v105
	v_pk_fma_f32 v[0:1], v[6:7], v[2:3], v[0:1]
	v_mul_f32_e32 v2, v7, v3
	s_waitcnt vmcnt(0)
	v_mfma_f32_32x32x16_bf16 v[34:49], v[50:53], v[102:105], v[34:49]
	ds_read_b128 v[50:53], v247
	ds_read_b128 v[54:57], v247 offset:32
	v_add_f32_e64 v232, v2, v0
	v_add_f32_e64 v233, v2, v1
	s_waitcnt lgkmcnt(1)
	v_sub_f32_e32 v50, v50, v210
	v_sub_f32_e32 v51, v51, v210
	v_mul_f32_e32 v50, 0x3fb8aa3b, v50
	v_mul_f32_e32 v51, 0x3fb8aa3b, v51
	v_exp_f32_e32 v50, v50
	v_exp_f32_e32 v51, v51
	v_mfma_f32_32x32x16_bf16 v[16:31], v[74:77], v[106:109], v[16:31]
	global_load_dwordx4 v[74:77], v[160:161], off offset:32
	v_mul_f32_e64 v50, v34, v50
	v_mul_f32_e64 v51, v35, v51
	v_add_f32_e32 v34, 0, v50
	v_add_f32_e32 v58, v51, v34
	v_sub_f32_e32 v34, v52, v210
	v_sub_f32_e32 v35, v53, v210
	v_mul_f32_e32 v34, 0x3fb8aa3b, v34
	v_mul_f32_e32 v35, 0x3fb8aa3b, v35
	v_exp_f32_e32 v34, v34
	v_exp_f32_e32 v35, v35
	v_mfma_f32_32x32x16_bf16 v[16:31], v[78:81], v[102:105], v[16:31]
	v_mul_f32_e64 v52, v36, v34
	v_mul_f32_e64 v53, v37, v35
	v_add_f32_e32 v34, v52, v58
	v_add_f32_e32 v36, v53, v34
	s_waitcnt lgkmcnt(0)
	v_sub_f32_e32 v34, v54, v210
	v_sub_f32_e32 v35, v55, v210
	v_mul_f32_e32 v34, 0x3fb8aa3b, v34
	v_mul_f32_e32 v35, 0x3fb8aa3b, v35
	v_exp_f32_e32 v34, v34
	v_exp_f32_e32 v35, v35
	v_mfma_f32_32x32x16_bf16 v[0:15], v[82:85], v[98:101], 0
	v_mul_f32_e64 v38, v38, v34
	v_mul_f32_e64 v39, v39, v35
	v_add_f32_e32 v34, v38, v36
	v_add_f32_e32 v36, v39, v34
	v_sub_f32_e32 v34, v56, v210
	v_sub_f32_e32 v35, v57, v210
	v_mul_f32_e32 v34, 0x3fb8aa3b, v34
	v_mul_f32_e32 v35, 0x3fb8aa3b, v35
	v_exp_f32_e32 v34, v34
	v_exp_f32_e32 v35, v35
	v_mfma_f32_32x32x16_bf16 v[0:15], v[86:89], v[110:113], v[0:15]
	v_lshl_add_u64 v[88:89], v[162:163], 0, v[164:165]
	v_mul_f32_e64 v40, v40, v34
	v_mul_f32_e64 v41, v41, v35
	v_add_f32_e32 v34, v40, v36
	v_add_f32_e32 v54, v41, v34
	ds_read_b128 v[34:37], v247 offset:64
	s_waitcnt lgkmcnt(0)
	v_sub_f32_e32 v34, v34, v210
	v_sub_f32_e32 v35, v35, v210
	v_mul_f32_e32 v34, 0x3fb8aa3b, v34
	v_mul_f32_e32 v35, 0x3fb8aa3b, v35
	v_exp_f32_e32 v34, v34
	v_exp_f32_e32 v35, v35
	v_mfma_f32_32x32x16_bf16 v[0:15], v[90:93], v[106:109], v[0:15]
	v_mul_f32_e64 v70, v42, v34
	v_mul_f32_e64 v71, v43, v35
	v_add_f32_e32 v34, v70, v54
	v_add_f32_e32 v42, v71, v34
	v_sub_f32_e32 v34, v36, v210
	v_sub_f32_e32 v35, v37, v210
	v_mul_f32_e32 v34, 0x3fb8aa3b, v34
	v_mul_f32_e32 v35, 0x3fb8aa3b, v35
	v_exp_f32_e32 v34, v34
	v_exp_f32_e32 v35, v35
	v_cvt_pk_bf16_f32 v70, v70, v71
	v_mfma_f32_32x32x16_bf16 v[0:15], v[94:97], v[102:105], v[0:15]
	v_mul_f32_e64 v72, v44, v34
	v_mul_f32_e64 v73, v45, v35
	v_add_f32_e32 v34, v72, v42
	v_add_f32_e32 v78, v73, v34
	ds_read_b128 v[34:37], v247 offset:96
	v_cvt_pk_bf16_f32 v71, v72, v73
	s_waitcnt lgkmcnt(0)
	v_sub_f32_e32 v34, v34, v210
	v_sub_f32_e32 v35, v35, v210
	v_mul_f32_e32 v34, 0x3fb8aa3b, v34
	v_mul_f32_e32 v35, 0x3fb8aa3b, v35
	v_exp_f32_e32 v34, v34
	v_exp_f32_e32 v35, v35
	s_nop 0
	v_pk_mul_f32 v[66:67], v[46:47], v[34:35]
	v_sub_f32_e32 v34, v36, v210
	v_sub_f32_e32 v35, v37, v210
	v_cvt_pk_bf16_f32 v36, v38, v39
	v_cvt_pk_bf16_f32 v37, v40, v41
	global_load_dwordx4 v[38:41], v[160:161], off
	v_mul_f32_e32 v34, 0x3fb8aa3b, v34
	v_mul_f32_e32 v35, 0x3fb8aa3b, v35
	v_exp_f32_e32 v34, v34
	v_exp_f32_e32 v35, v35
	v_cvt_pk_bf16_f32 v72, v66, v67
	v_add_f32_e32 v66, v66, v78
	v_add_f32_e32 v66, v67, v66
	v_pk_mul_f32 v[68:69], v[48:49], v[34:35]
	v_cvt_pk_bf16_f32 v34, v50, v51
	v_cvt_pk_bf16_f32 v35, v52, v53
	v_cvt_pk_bf16_f32 v73, v68, v69
	v_add_f32_e32 v66, v68, v66
	s_waitcnt vmcnt(0)
; #define MFMA32(a, b, c) __builtin_amdgcn_mfma_f32_32x32x16_bf16((a), (b), (c), 0, 0, 0)
; DI float fexp(float x) { return ex2(x * LOG2E); }
; DI void b3_phase(const bf16_t* P, const bf16_t* BQ, const bf16_t* BK, const bf16_t* VtB, const float* DC, const float* SC, const float* gate_bias, const float* onorm, bf16_t* Y, unsigned char* lds, int tid) {
;     ...
;       for (int tk = 0; tk < 2; ++tk) {
;         if (tk <= tq) {
;           f32x16 S = splat16(0.f);
; #pragma unroll
;           for (int ks = 0; ks < 4; ++ks) { const bf16x8 kf = *(const bf16x8*)(BK + (tok0 + 32 * tk + r32) * 256 + h * 64 + 16 * ks + 8 * hi); S = MFMA32(kf, qf[ks], S); }
;           asm volatile("" ::: "memory");
; #pragma unroll
;           for (int g4 = 0; g4 < 4; ++g4) { const f32x4 rv = *(const f32x4*)(R + 32 * tk + 8 * g4 + 4 * hi);
; #pragma unroll
;             for (int j = 0; j < 4; ++j) { const int s = 32 * tk + 8 * g4 + 4 * hi + j; const float w = (s <= t) ? fexp(rv[j] - mu_t) : 0.f; const float val = S[4 * g4 + j] * w; dsum += val; S[4 * g4 + j] = val; } }
; #pragma unroll
;           for (int kk = 0; kk < 2; ++kk) { const bf16x8 pf = pack8(S, kk);
; #pragma unroll
;             for (int eb = 0; eb < 2; ++eb) { const bf16_t* vp = VtB + (((size_t)bh * 256 + c) * 64 + 32 * eb + r32) * 64 + 32 * tk + 16 * kk + 8 * hi;
;               const bf16x8 vf = *(const bf16x8*)vp; num[eb] = MFMA32(vf, pf, num[eb]); } }
;           asm volatile("" ::: "memory");
;         }
;       }
;       dsum += __shfl_xor(dsum, 32);
	v_mfma_f32_32x32x16_bf16 v[50:65], v[38:41], v[34:37], 0
	global_load_dwordx4 v[38:41], v[168:169], off
	v_add_f32_e32 v82, v69, v66
	v_mfma_f32_32x32x16_bf16 v[50:65], v[74:77], v[70:73], v[50:65]
	global_load_dwordx4 v[74:77], v[166:167], off
	global_load_dwordx4 v[66:69], v[88:89], off
	global_load_dwordx4 v[84:87], v[88:89], off offset:32
	s_waitcnt vmcnt(3)
	v_mfma_f32_32x32x16_bf16 v[34:49], v[38:41], v[34:37], 0
	s_waitcnt vmcnt(2)
	v_mfma_f32_32x32x16_bf16 v[34:49], v[74:77], v[70:73], v[34:49]
	s_waitcnt vmcnt(1)
	v_mfma_f32_32x32x16_bf16 v[66:81], v[66:69], v[98:101], 0
	s_waitcnt vmcnt(0)
	v_mfma_f32_32x32x16_bf16 v[66:81], v[84:87], v[110:113], v[66:81]
	global_load_dwordx4 v[84:87], v[88:89], off offset:64
	s_waitcnt vmcnt(0)
	v_mfma_f32_32x32x16_bf16 v[66:81], v[84:87], v[106:109], v[66:81]
	global_load_dwordx4 v[84:87], v[88:89], off offset:96
	s_waitcnt vmcnt(0)
	v_mfma_f32_32x32x16_bf16 v[66:81], v[84:87], v[102:105], v[66:81]
	ds_read_b128 v[84:87], v247 offset:128
	ds_read_b128 v[88:91], v247 offset:160
	s_waitcnt lgkmcnt(1)
	v_sub_f32_e32 v83, v84, v210
	v_sub_f32_e32 v84, v85, v210
	v_mul_f32_e32 v84, 0x3fb8aa3b, v84
	v_exp_f32_e32 v84, v84
	v_sub_f32_e32 v85, v87, v210
	v_mul_f32_e32 v85, 0x3fb8aa3b, v85
	v_exp_f32_e32 v85, v85
	v_cndmask_b32_e64 v93, v84, 0, s[50:51]
	v_sub_f32_e32 v84, v86, v210
	v_mul_f32_e32 v84, 0x3fb8aa3b, v84
	v_exp_f32_e32 v84, v84
	v_cndmask_b32_e64 v85, v85, 0, s[52:53]
	v_mul_f32_e32 v83, 0x3fb8aa3b, v83
	v_exp_f32_e32 v83, v83
	v_cndmask_b32_e64 v84, v84, 0, s[54:55]
	v_pk_mul_f32 v[68:69], v[68:69], v[84:85]
	s_waitcnt lgkmcnt(0)
	v_sub_f32_e32 v84, v88, v210
	v_sub_f32_e32 v85, v89, v210
	v_mul_f32_e32 v84, 0x3fb8aa3b, v84
	v_mul_f32_e32 v85, 0x3fb8aa3b, v85
	v_exp_f32_e32 v84, v84
	v_exp_f32_e32 v85, v85
	v_cndmask_b32_e64 v83, v83, 0, s[16:17]
	v_mul_f32_e32 v92, v66, v83
	v_cndmask_b32_e64 v84, v84, 0, s[58:59]
	v_cndmask_b32_e64 v85, v85, 0, s[56:57]
	v_pk_mul_f32 v[70:71], v[70:71], v[84:85]
	v_sub_f32_e32 v84, v90, v210
	v_sub_f32_e32 v85, v91, v210
	v_mul_f32_e32 v84, 0x3fb8aa3b, v84
	v_mul_f32_e32 v85, 0x3fb8aa3b, v85
	v_exp_f32_e32 v84, v84
	v_exp_f32_e32 v85, v85
	v_mul_f32_e32 v94, v67, v93
	v_fmac_f32_e32 v82, v66, v83
	v_cndmask_b32_e64 v84, v84, 0, s[62:63]
	v_cndmask_b32_e64 v85, v85, 0, s[60:61]
	v_pk_mul_f32 v[72:73], v[72:73], v[84:85]
	ds_read_b128 v[84:87], v247 offset:192
	v_fmac_f32_e32 v82, v67, v93
	v_add_f32_e32 v66, v68, v82
	v_add_f32_e32 v66, v69, v66
	v_add_f32_e32 v227, v70, v66
	s_waitcnt lgkmcnt(0)
	v_sub_f32_e32 v84, v84, v210
	v_sub_f32_e32 v85, v85, v210
	v_mul_f32_e32 v84, 0x3fb8aa3b, v84
	v_mul_f32_e32 v85, 0x3fb8aa3b, v85
	v_exp_f32_e32 v84, v84
	v_exp_f32_e32 v85, v85
	v_mov_b32_e32 v213, v71
	v_pk_add_f32 v[66:67], v[212:213], v[226:227]
	v_cndmask_b32_e64 v84, v84, 0, s[66:67]
	v_cndmask_b32_e64 v85, v85, 0, s[64:65]
	v_pk_mul_f32 v[84:85], v[74:75], v[84:85]
	v_sub_f32_e32 v74, v86, v210
	v_sub_f32_e32 v75, v87, v210
	v_mul_f32_e32 v74, 0x3fb8aa3b, v74
	v_mul_f32_e32 v75, 0x3fb8aa3b, v75
	v_exp_f32_e32 v74, v74
	v_exp_f32_e32 v75, v75
	v_mov_b32_e32 v225, v72
	v_pk_add_f32 v[66:67], v[224:225], v[66:67]
	v_cndmask_b32_e64 v74, v74, 0, s[70:71]
	v_cndmask_b32_e64 v75, v75, 0, s[68:69]
	v_pk_mul_f32 v[86:87], v[76:77], v[74:75]
	ds_read_b128 v[74:77], v247 offset:224
	v_mov_b32_e32 v223, v73
	v_pk_add_f32 v[66:67], v[222:223], v[66:67]
	v_mov_b32_e32 v221, v84
	v_pk_add_f32 v[66:67], v[220:221], v[66:67]
	s_waitcnt lgkmcnt(0)
	v_sub_f32_e32 v74, v74, v210
	v_sub_f32_e32 v75, v75, v210
	v_mul_f32_e32 v74, 0x3fb8aa3b, v74
	v_mul_f32_e32 v75, 0x3fb8aa3b, v75
	v_exp_f32_e32 v74, v74
	v_exp_f32_e32 v75, v75
	v_mov_b32_e32 v219, v85
	v_pk_add_f32 v[66:67], v[218:219], v[66:67]
	v_cndmask_b32_e64 v74, v74, 0, s[74:75]
	v_cndmask_b32_e64 v75, v75, 0, s[72:73]
	v_pk_mul_f32 v[88:89], v[78:79], v[74:75]
	v_sub_f32_e32 v74, v76, v210
	v_sub_f32_e32 v75, v77, v210
	v_mul_f32_e32 v74, 0x3fb8aa3b, v74
	v_mul_f32_e32 v75, 0x3fb8aa3b, v75
	v_exp_f32_e32 v74, v74
	v_exp_f32_e32 v75, v75
	v_cvt_pk_bf16_f32 v76, v70, v71
	v_cvt_pk_bf16_f32 v77, v72, v73
	v_cndmask_b32_e64 v74, v74, 0, s[78:79]
	v_cndmask_b32_e64 v75, v75, 0, s[76:77]
	v_pk_mul_f32 v[90:91], v[80:81], v[74:75]
	global_load_dwordx4 v[78:81], v[160:161], off offset:64
	v_cvt_pk_bf16_f32 v74, v92, v94
	v_cvt_pk_bf16_f32 v75, v68, v69
	v_mov_b32_e32 v217, v86
	v_pk_add_f32 v[66:67], v[216:217], v[66:67]
	s_waitcnt vmcnt(0)
	v_mfma_f32_32x32x16_bf16 v[50:65], v[78:81], v[74:77], v[50:65]
	v_lshl_add_u64 v[78:79], v[142:143], 0, v[158:159]
	global_load_dwordx4 v[78:81], v[78:79], off
	v_mov_b32_e32 v215, v87
	v_add_f32_e64 v66, v214, v66
	v_add_f32_e64 v67, v215, v67
	v_mov_b32_e32 v68, v33
	v_mov_b32_e32 v69, v88
	v_pk_add_f32 v[66:67], v[68:69], v[66:67]
	s_waitcnt vmcnt(0)
	v_mfma_f32_32x32x16_bf16 v[34:49], v[78:81], v[74:77], v[34:49]
	global_load_dwordx4 v[78:81], v[160:161], off offset:96
	v_cvt_pk_bf16_f32 v74, v84, v85
	v_cvt_pk_bf16_f32 v75, v86, v87
	v_cvt_pk_bf16_f32 v76, v88, v89
	v_cvt_pk_bf16_f32 v77, v90, v91
	v_mov_b32_e32 v229, v89
	v_pk_add_f32 v[66:67], v[228:229], v[66:67]
	s_waitcnt vmcnt(0)
	v_mfma_f32_32x32x16_bf16 v[50:65], v[78:81], v[74:77], v[50:65]
	v_lshl_add_u64 v[78:79], v[144:145], 0, v[158:159]
	global_load_dwordx4 v[78:81], v[78:79], off
	v_mov_b32_e32 v231, v90
	v_add_f32_e64 v66, v230, v66
	v_add_f32_e64 v67, v231, v67
	v_mov_b32_e32 v233, v91
	v_pk_add_f32 v[66:67], v[232:233], v[66:67]
	ds_bpermute_b32 v68, v141, v66
	ds_bpermute_b32 v69, v141, v67
	s_waitcnt vmcnt(0)
	v_mfma_f32_32x32x16_bf16 v[34:49], v[78:81], v[74:77], v[34:49]
	s_waitcnt lgkmcnt(0)
; DI void b3_phase(const bf16_t* P, const bf16_t* BQ, const bf16_t* BK, const bf16_t* VtB, const float* DC, const float* SC, const float* gate_bias, const float* onorm, bf16_t* Y, unsigned char* lds, int tid) {
;     ...
;       dsum += __shfl_xor(dsum, 32);
;       const float den = si_t * qn + dsum, inv = 1.0f / fmaxf(fabsf(den), em_t);
;       float ss = 0.f;
; #pragma unroll
;       for (int eb = 0; eb < 2; ++eb)
; #pragma unroll
;         for (int i = 0; i < 16; ++i) { const float hv = (num[eb][i] + si_t * G[eb][i]) * inv; num[eb][i] = hv; ss += hv * hv; }
;       ss += __shfl_xor(ss, 32);
;       const float rstd = rsqrtf(ss * (1.f / 64.f) + EPS_);
	v_add_f32_e64 v66, v66, v68
	v_add_f32_e64 v67, v67, v69
	v_fmac_f32_e32 v67, v211, v66
	v_max_f32_e32 v66, v149, v149
	v_max_f32_e64 v66, |v67|, v66
	v_div_scale_f32 v67, s[2:3], v66, v66, 1.0
	v_rcp_f32_e32 v68, v67
	s_nop 0
	v_fma_f32 v69, -v67, v68, 1.0
	v_fmac_f32_e32 v68, v69, v68
	v_div_scale_f32 v69, vcc, 1.0, v66, 1.0
	v_mul_f32_e32 v70, v69, v68
	v_fma_f32 v71, -v67, v70, v69
	v_fmac_f32_e32 v70, v71, v68
	v_fma_f32 v67, -v67, v70, v69
	v_div_fmas_f32 v67, v67, v68, v70
	v_mov_b32_e32 v70, v211
	v_div_fixup_f32 v68, v67, v66, 1.0
	v_pk_fma_f32 v[10:11], v[70:71], v[10:11], v[44:45] op_sel_hi:[0,1,1]
	v_pk_mul_f32 v[66:67], v[10:11], v[68:69] op_sel_hi:[1,0]
	v_pk_fma_f32 v[10:11], v[70:71], v[12:13], v[46:47] op_sel_hi:[0,1,1]
	v_mad_u64_u32 v[12:13], s[2:3], v156, s82, v[154:155]
	v_mad_i32_i24 v13, v153, s82, v13
	v_pk_mul_f32 v[44:45], v[10:11], v[68:69] op_sel_hi:[1,0]
	v_pk_fma_f32 v[10:11], v[70:71], v[14:15], v[48:49] op_sel_hi:[0,1,1]
	v_lshl_add_u64 v[14:15], v[12:13], 0, v[32:33]
	v_lshl_add_u64 v[78:79], v[14:15], 0, v[174:175]
	global_load_dwordx2 v[80:81], v[78:79], off offset:3072
	global_load_dwordx4 v[46:49], v[172:173], off
	v_lshlrev_b64 v[12:13], 11, v[156:157]
	v_lshl_add_u64 v[12:13], s[0:1], 0, v[12:13]
	v_lshl_add_u64 v[12:13], v[12:13], 0, v[32:33]
	v_pk_fma_f32 v[16:17], v[70:71], v[16:17], v[50:51] op_sel_hi:[0,1,1]
	v_pk_fma_f32 v[18:19], v[70:71], v[18:19], v[52:53] op_sel_hi:[0,1,1]
	v_pk_mul_f32 v[16:17], v[16:17], v[68:69] op_sel_hi:[1,0]
	v_pk_mul_f32 v[18:19], v[18:19], v[68:69] op_sel_hi:[1,0]
	v_pk_mul_f32 v[50:51], v[16:17], v[16:17]
	v_pk_mul_f32 v[52:53], v[18:19], v[18:19]
	v_pk_fma_f32 v[20:21], v[70:71], v[20:21], v[54:55] op_sel_hi:[0,1,1]
	v_pk_mul_f32 v[20:21], v[20:21], v[68:69] op_sel_hi:[1,0]
	v_pk_fma_f32 v[22:23], v[70:71], v[22:23], v[56:57] op_sel_hi:[0,1,1]
	v_pk_mul_f32 v[54:55], v[20:21], v[20:21]
	v_pk_mul_f32 v[22:23], v[22:23], v[68:69] op_sel_hi:[1,0]
	v_pk_fma_f32 v[24:25], v[70:71], v[24:25], v[58:59] op_sel_hi:[0,1,1]
	v_pk_mul_f32 v[56:57], v[22:23], v[22:23]
	v_pk_mul_f32 v[24:25], v[24:25], v[68:69] op_sel_hi:[1,0]
	v_pk_fma_f32 v[26:27], v[70:71], v[26:27], v[60:61] op_sel_hi:[0,1,1]
	v_pk_mul_f32 v[58:59], v[24:25], v[24:25]
	v_pk_mul_f32 v[26:27], v[26:27], v[68:69] op_sel_hi:[1,0]
	v_pk_fma_f32 v[28:29], v[70:71], v[28:29], v[62:63] op_sel_hi:[0,1,1]
	v_pk_mul_f32 v[60:61], v[26:27], v[26:27]
	v_pk_mul_f32 v[28:29], v[28:29], v[68:69] op_sel_hi:[1,0]
	v_pk_fma_f32 v[30:31], v[70:71], v[30:31], v[64:65] op_sel_hi:[0,1,1]
	v_pk_mul_f32 v[62:63], v[28:29], v[28:29]
	v_pk_mul_f32 v[30:31], v[30:31], v[68:69] op_sel_hi:[1,0]
	v_pk_fma_f32 v[0:1], v[70:71], v[0:1], v[34:35] op_sel_hi:[0,1,1]
	v_pk_mul_f32 v[64:65], v[30:31], v[30:31]
	v_pk_mul_f32 v[34:35], v[0:1], v[68:69] op_sel_hi:[1,0]
	v_pk_fma_f32 v[2:3], v[70:71], v[2:3], v[36:37] op_sel_hi:[0,1,1]
	v_pk_mul_f32 v[0:1], v[34:35], v[34:35]
	v_pk_mul_f32 v[36:37], v[2:3], v[68:69] op_sel_hi:[1,0]
	v_pk_fma_f32 v[4:5], v[70:71], v[4:5], v[38:39] op_sel_hi:[0,1,1]
	v_pk_mul_f32 v[2:3], v[36:37], v[36:37]
	v_pk_mul_f32 v[4:5], v[4:5], v[68:69] op_sel_hi:[1,0]
	v_pk_fma_f32 v[6:7], v[70:71], v[6:7], v[40:41] op_sel_hi:[0,1,1]
	v_pk_mul_f32 v[38:39], v[4:5], v[4:5]
	v_pk_mul_f32 v[6:7], v[6:7], v[68:69] op_sel_hi:[1,0]
	v_pk_fma_f32 v[8:9], v[70:71], v[8:9], v[42:43] op_sel_hi:[0,1,1]
	v_pk_mul_f32 v[40:41], v[6:7], v[6:7]
	v_pk_mul_f32 v[8:9], v[8:9], v[68:69] op_sel_hi:[1,0]
	v_pk_mul_f32 v[72:73], v[66:67], v[66:67]
	v_pk_mul_f32 v[42:43], v[8:9], v[8:9]
	v_pk_mul_f32 v[74:75], v[44:45], v[44:45]
	v_pk_mul_f32 v[10:11], v[10:11], v[68:69] op_sel_hi:[1,0]
	v_lshl_add_u64 v[84:85], v[12:13], 0, v[174:175]
	v_pk_mul_f32 v[76:77], v[10:11], v[10:11]
	v_lshl_add_u64 v[86:87], v[14:15], 0, v[182:183]
	v_lshl_add_u64 v[88:89], v[12:13], 0, v[182:183]
	v_lshl_add_u64 v[90:91], v[14:15], 0, v[190:191]
	v_lshl_add_u64 v[92:93], v[12:13], 0, v[190:191]
	v_lshl_add_u64 v[94:95], v[14:15], 0, v[192:193]
	v_lshl_add_u64 v[96:97], v[12:13], 0, v[192:193]
	v_lshl_add_u64 v[98:99], v[14:15], 0, v[204:205]
	v_lshl_add_u64 v[100:101], v[12:13], 0, v[204:205]
	v_lshl_add_u64 v[102:103], v[14:15], 0, v[184:185]
	s_waitcnt vmcnt(1)
	v_lshlrev_b32_e32 v32, 16, v80
	v_mul_f32_e32 v32, 0xbfb8aa3b, v32
	v_exp_f32_e32 v32, v32
	s_nop 0
	v_add_f32_e32 v32, 1.0, v32
	v_rcp_f32_e32 v82, v32
	v_and_b32_e32 v32, 0xffff0000, v80
	v_mul_f32_e32 v32, 0xbfb8aa3b, v32
	v_exp_f32_e32 v32, v32
	s_nop 0
	v_add_f32_e32 v32, 1.0, v32
	v_rcp_f32_e32 v83, v32
	v_lshlrev_b32_e32 v32, 16, v81
	v_mul_f32_e32 v32, 0xbfb8aa3b, v32
	v_exp_f32_e32 v32, v32
	s_nop 0
	v_add_f32_e32 v32, 1.0, v32
	v_rcp_f32_e32 v80, v32
	v_and_b32_e32 v32, 0xffff0000, v81
	v_mul_f32_e32 v32, 0xbfb8aa3b, v32
	v_exp_f32_e32 v32, v32
	s_nop 0
	v_add_f32_e32 v32, 1.0, v32
	v_rcp_f32_e32 v81, v32
	v_add_f32_e32 v32, v50, v51
	v_add_f32_e32 v32, v52, v32
	v_add_f32_e32 v32, v53, v32
	v_add_f32_e32 v32, v54, v32
	v_add_f32_e32 v32, v55, v32
	v_add_f32_e32 v32, v56, v32
	v_add_f32_e32 v32, v57, v32
	v_add_f32_e32 v32, v58, v32
	v_add_f32_e32 v32, v59, v32
	v_add_f32_e32 v32, v60, v32
	v_add_f32_e32 v32, v61, v32
	v_add_f32_e32 v32, v62, v32
	v_add_f32_e32 v32, v63, v32
	v_add_f32_e32 v32, v64, v32
	v_add_f32_e32 v32, v65, v32
	v_add_f32_e32 v0, v0, v32
	v_add_f32_e32 v0, v1, v0
	v_add_f32_e32 v0, v2, v0
	v_add_f32_e32 v0, v3, v0
	v_add_f32_e32 v0, v38, v0
	v_add_f32_e32 v0, v39, v0
	v_add_f32_e32 v0, v40, v0
	v_add_f32_e32 v0, v41, v0
	v_add_f32_e32 v0, v42, v0
	v_add_f32_e32 v0, v43, v0
	v_add_f32_e32 v0, v72, v0
	v_add_f32_e32 v0, v73, v0
	v_add_f32_e32 v0, v74, v0
	v_add_f32_e32 v0, v75, v0
	v_add_f32_e32 v0, v76, v0
	v_add_f32_e32 v0, v77, v0
	ds_bpermute_b32 v1, v141, v0
	s_waitcnt lgkmcnt(0)
; DI unsigned pk2(float a, float b) { return pg8::cvt_pk_bf16(a, b); }
; DI float bflo(unsigned w) { return __uint_as_float(w << 16); }
; DI float bfhi(unsigned w) { return __uint_as_float(w & 0xffff0000u); }
; DI float rcpf_(float x) { return __builtin_amdgcn_rcpf(x); }
; DI float fexp(float x) { return ex2(x * LOG2E); }
; DI void b3_phase(const bf16_t* P, const bf16_t* BQ, const bf16_t* BK, const bf16_t* VtB, const float* DC, const float* SC, const float* gate_bias, const float* onorm, bf16_t* Y, unsigned char* lds, int tid) {
;     ...
;   for (int item = blockIdx.x * 8 + wave; item < 2048; item += gridDim.x * 8) {
;     ...
;       const float rstd = rsqrtf(ss * (1.f / 64.f) + EPS_);
;       const bf16_t* bo = P + (tok0 + t) * PLD + C_BO + h * 64; bf16_t* yo = Y + (tok0 + t) * DM + 256 + h * 64;
; #pragma unroll
;       for (int eb = 0; eb < 2; ++eb)
; #pragma unroll
;         for (int g4 = 0; g4 < 4; ++g4) { const int e = 32 * eb + 8 * g4 + 4 * hi; const u32x2 bw = *(const u32x2*)(bo + e); const f32x4 gn = *(const f32x4*)(onorm + h * 64 + e);
;           const float o0 = num[eb][4 * g4] * rstd * gn.x * rcpf_(1.f + fexp(-bflo(bw.x))), o1 = num[eb][4 * g4 + 1] * rstd * gn.y * rcpf_(1.f + fexp(-bfhi(bw.x)));
;           const float o2 = num[eb][4 * g4 + 2] * rstd * gn.z * rcpf_(1.f + fexp(-bflo(bw.y))), o3 = num[eb][4 * g4 + 3] * rstd * gn.w * rcpf_(1.f + fexp(-bfhi(bw.y)));
;           u32x2 ow; ow.x = pk2(o0, o1); ow.y = pk2(o2, o3); *(u32x2*)(yo + e) = ow; }
	v_add_f32_e32 v0, v0, v1
	v_fmamk_f32 v0, v0, 0x3c800000, v237
	v_cmp_gt_f32_e32 vcc, s97, v0
	v_mul_f32_e32 v1, 0x4b800000, v0
	s_nop 0
	v_cndmask_b32_e32 v0, v0, v1, vcc
	v_rsq_f32_e32 v0, v0
	s_nop 0
	v_mul_f32_e32 v1, 0x45800000, v0
	v_cndmask_b32_e32 v32, v0, v1, vcc
	v_pk_mul_f32 v[0:1], v[16:17], v[32:33] op_sel_hi:[1,0]
	v_pk_mul_f32 v[2:3], v[18:19], v[32:33] op_sel_hi:[1,0]
	s_waitcnt vmcnt(0)
	v_pk_mul_f32 v[0:1], v[46:47], v[0:1]
	v_pk_mul_f32 v[2:3], v[48:49], v[2:3]
	v_pk_mul_f32 v[0:1], v[82:83], v[0:1]
	v_pk_mul_f32 v[2:3], v[80:81], v[2:3]
	v_cvt_pk_bf16_f32 v0, v0, v1
	v_cvt_pk_bf16_f32 v1, v2, v3
	global_store_dwordx2 v[84:85], v[0:1], off offset:512
	global_load_dwordx2 v[16:17], v[86:87], off offset:3072
	s_nop 0
	global_load_dwordx4 v[0:3], v[176:177], off
	v_pk_mul_f32 v[20:21], v[20:21], v[32:33] op_sel_hi:[1,0]
	v_pk_mul_f32 v[4:5], v[4:5], v[32:33] op_sel_hi:[1,0]
	v_pk_mul_f32 v[6:7], v[6:7], v[32:33] op_sel_hi:[1,0]
	v_pk_mul_f32 v[8:9], v[8:9], v[32:33] op_sel_hi:[1,0]
	v_cmp_lt_i32_e32 vcc, s21, v115
	s_or_b64 s[90:91], vcc, s[90:91]
	s_waitcnt vmcnt(1)
	v_lshlrev_b32_e32 v18, 16, v16
	v_and_b32_e32 v16, 0xffff0000, v16
	v_mul_f32_e32 v16, 0xbfb8aa3b, v16
	v_exp_f32_e32 v16, v16
	v_mul_f32_e32 v18, 0xbfb8aa3b, v18
	v_exp_f32_e32 v18, v18
	s_waitcnt vmcnt(0)
	v_pk_mul_f32 v[0:1], v[0:1], v[20:21]
	v_add_f32_e32 v16, 1.0, v16
	v_rcp_f32_e32 v19, v16
	v_lshlrev_b32_e32 v16, 16, v17
	v_and_b32_e32 v17, 0xffff0000, v17
	v_mul_f32_e32 v16, 0xbfb8aa3b, v16
	v_mul_f32_e32 v17, 0xbfb8aa3b, v17
	v_exp_f32_e32 v16, v16
	v_exp_f32_e32 v17, v17
	v_add_f32_e32 v18, 1.0, v18
	v_rcp_f32_e32 v18, v18
	v_add_f32_e32 v16, 1.0, v16
	v_add_f32_e32 v17, 1.0, v17
	v_rcp_f32_e32 v16, v16
	v_rcp_f32_e32 v17, v17
	v_pk_mul_f32 v[0:1], v[18:19], v[0:1]
	v_pk_mul_f32 v[18:19], v[22:23], v[32:33] op_sel_hi:[1,0]
	v_cvt_pk_bf16_f32 v0, v0, v1
	v_pk_mul_f32 v[2:3], v[2:3], v[18:19]
	v_pk_mul_f32 v[20:21], v[24:25], v[32:33] op_sel_hi:[1,0]
	v_pk_mul_f32 v[2:3], v[16:17], v[2:3]
	s_nop 0
	v_cvt_pk_bf16_f32 v1, v2, v3
	global_store_dwordx2 v[88:89], v[0:1], off offset:512
	global_load_dwordx2 v[16:17], v[90:91], off offset:3072
	s_nop 0
	global_load_dwordx4 v[0:3], v[178:179], off
	s_waitcnt vmcnt(1)
	v_lshlrev_b32_e32 v18, 16, v16
	v_and_b32_e32 v16, 0xffff0000, v16
	v_mul_f32_e32 v16, 0xbfb8aa3b, v16
	v_exp_f32_e32 v16, v16
	v_mul_f32_e32 v18, 0xbfb8aa3b, v18
	v_exp_f32_e32 v18, v18
	s_waitcnt vmcnt(0)
	v_pk_mul_f32 v[0:1], v[0:1], v[20:21]
	v_add_f32_e32 v16, 1.0, v16
	v_rcp_f32_e32 v19, v16
	v_lshlrev_b32_e32 v16, 16, v17
	v_and_b32_e32 v17, 0xffff0000, v17
	v_mul_f32_e32 v16, 0xbfb8aa3b, v16
	v_mul_f32_e32 v17, 0xbfb8aa3b, v17
	v_exp_f32_e32 v16, v16
	v_exp_f32_e32 v17, v17
	v_add_f32_e32 v18, 1.0, v18
	v_rcp_f32_e32 v18, v18
	v_add_f32_e32 v16, 1.0, v16
	v_add_f32_e32 v17, 1.0, v17
	v_rcp_f32_e32 v16, v16
	v_rcp_f32_e32 v17, v17
	v_pk_mul_f32 v[0:1], v[18:19], v[0:1]
	v_pk_mul_f32 v[18:19], v[26:27], v[32:33] op_sel_hi:[1,0]
	v_cvt_pk_bf16_f32 v0, v0, v1
	v_pk_mul_f32 v[2:3], v[2:3], v[18:19]
	v_pk_mul_f32 v[20:21], v[28:29], v[32:33] op_sel_hi:[1,0]
	v_pk_mul_f32 v[2:3], v[16:17], v[2:3]
	s_nop 0
	v_cvt_pk_bf16_f32 v1, v2, v3
	global_store_dwordx2 v[92:93], v[0:1], off offset:512
	global_load_dwordx2 v[16:17], v[94:95], off offset:3072
	s_nop 0
	global_load_dwordx4 v[0:3], v[180:181], off
	s_waitcnt vmcnt(1)
	v_lshlrev_b32_e32 v18, 16, v16
	v_and_b32_e32 v16, 0xffff0000, v16
	v_mul_f32_e32 v16, 0xbfb8aa3b, v16
	v_exp_f32_e32 v16, v16
	v_mul_f32_e32 v18, 0xbfb8aa3b, v18
	v_exp_f32_e32 v18, v18
	s_waitcnt vmcnt(0)
	v_pk_mul_f32 v[0:1], v[0:1], v[20:21]
	v_add_f32_e32 v16, 1.0, v16
	v_rcp_f32_e32 v19, v16
	v_lshlrev_b32_e32 v16, 16, v17
	v_and_b32_e32 v17, 0xffff0000, v17
	v_mul_f32_e32 v16, 0xbfb8aa3b, v16
	v_mul_f32_e32 v17, 0xbfb8aa3b, v17
	v_exp_f32_e32 v16, v16
	v_exp_f32_e32 v17, v17
	v_add_f32_e32 v18, 1.0, v18
	v_rcp_f32_e32 v18, v18
	v_add_f32_e32 v16, 1.0, v16
	v_add_f32_e32 v17, 1.0, v17
	v_rcp_f32_e32 v16, v16
	v_rcp_f32_e32 v17, v17
	v_pk_mul_f32 v[0:1], v[18:19], v[0:1]
	v_pk_mul_f32 v[18:19], v[30:31], v[32:33] op_sel_hi:[1,0]
	v_cvt_pk_bf16_f32 v0, v0, v1
	v_pk_mul_f32 v[2:3], v[2:3], v[18:19]
	v_pk_mul_f32 v[20:21], v[34:35], v[32:33] op_sel_hi:[1,0]
	v_pk_mul_f32 v[2:3], v[16:17], v[2:3]
	s_nop 0
	v_cvt_pk_bf16_f32 v1, v2, v3
	global_store_dwordx2 v[96:97], v[0:1], off offset:512
	global_load_dwordx2 v[16:17], v[78:79], off offset:3136
	s_nop 0
	global_load_dwordx4 v[0:3], v[172:173], off offset:128
	s_waitcnt vmcnt(1)
; DI unsigned pk2(float a, float b) { return pg8::cvt_pk_bf16(a, b); }
; DI float bflo(unsigned w) { return __uint_as_float(w << 16); }
; DI float bfhi(unsigned w) { return __uint_as_float(w & 0xffff0000u); }
; DI float rcpf_(float x) { return __builtin_amdgcn_rcpf(x); }
; DI float fexp(float x) { return ex2(x * LOG2E); }
; DI void lds_wave_sync() { asm volatile("s_waitcnt lgkmcnt(0)" ::: "memory"); __builtin_amdgcn_wave_barrier(); }
; DI void b3_phase(const bf16_t* P, const bf16_t* BQ, const bf16_t* BK, const bf16_t* VtB, const float* DC, const float* SC, const float* gate_bias, const float* onorm, bf16_t* Y, unsigned char* lds, int tid) {
;     ...
;       for (int eb = 0; eb < 2; ++eb)
; #pragma unroll
;         for (int g4 = 0; g4 < 4; ++g4) { const int e = 32 * eb + 8 * g4 + 4 * hi; const u32x2 bw = *(const u32x2*)(bo + e); const f32x4 gn = *(const f32x4*)(onorm + h * 64 + e);
;           const float o0 = num[eb][4 * g4] * rstd * gn.x * rcpf_(1.f + fexp(-bflo(bw.x))), o1 = num[eb][4 * g4 + 1] * rstd * gn.y * rcpf_(1.f + fexp(-bfhi(bw.x)));
;           const float o2 = num[eb][4 * g4 + 2] * rstd * gn.z * rcpf_(1.f + fexp(-bflo(bw.y))), o3 = num[eb][4 * g4 + 3] * rstd * gn.w * rcpf_(1.f + fexp(-bfhi(bw.y)));
;           u32x2 ow; ow.x = pk2(o0, o1); ow.y = pk2(o2, o3); *(u32x2*)(yo + e) = ow; }
;     }
;     lds_wave_sync();
;   }
	v_lshlrev_b32_e32 v18, 16, v16
	v_and_b32_e32 v16, 0xffff0000, v16
	v_mul_f32_e32 v16, 0xbfb8aa3b, v16
	v_exp_f32_e32 v16, v16
	v_mul_f32_e32 v18, 0xbfb8aa3b, v18
	v_exp_f32_e32 v18, v18
	s_waitcnt vmcnt(0)
	v_pk_mul_f32 v[0:1], v[0:1], v[20:21]
	v_add_f32_e32 v16, 1.0, v16
	v_rcp_f32_e32 v19, v16
	v_lshlrev_b32_e32 v16, 16, v17
	v_and_b32_e32 v17, 0xffff0000, v17
	v_mul_f32_e32 v16, 0xbfb8aa3b, v16
	v_mul_f32_e32 v17, 0xbfb8aa3b, v17
	v_exp_f32_e32 v16, v16
	v_exp_f32_e32 v17, v17
	v_add_f32_e32 v18, 1.0, v18
	v_rcp_f32_e32 v18, v18
	v_add_f32_e32 v16, 1.0, v16
	v_add_f32_e32 v17, 1.0, v17
	v_rcp_f32_e32 v16, v16
	v_rcp_f32_e32 v17, v17
	v_pk_mul_f32 v[0:1], v[18:19], v[0:1]
	v_pk_mul_f32 v[18:19], v[36:37], v[32:33] op_sel_hi:[1,0]
	v_cvt_pk_bf16_f32 v0, v0, v1
	v_pk_mul_f32 v[2:3], v[2:3], v[18:19]
	s_nop 0
	v_pk_mul_f32 v[2:3], v[16:17], v[2:3]
	s_nop 0
	v_cvt_pk_bf16_f32 v1, v2, v3
	global_store_dwordx2 v[84:85], v[0:1], off offset:576
	global_load_dwordx2 v[16:17], v[98:99], off offset:3072
	s_nop 0
	global_load_dwordx4 v[0:3], v[186:187], off
	s_waitcnt vmcnt(1)
	v_lshlrev_b32_e32 v18, 16, v16
	s_waitcnt vmcnt(0)
	v_pk_mul_f32 v[0:1], v[0:1], v[4:5]
	v_and_b32_e32 v4, 0xffff0000, v16
	v_mul_f32_e32 v4, 0xbfb8aa3b, v4
	v_exp_f32_e32 v4, v4
	v_and_b32_e32 v5, 0xffff0000, v17
	v_mul_f32_e32 v18, 0xbfb8aa3b, v18
	v_mul_f32_e32 v5, 0xbfb8aa3b, v5
	v_add_f32_e32 v4, 1.0, v4
	v_rcp_f32_e32 v19, v4
	v_lshlrev_b32_e32 v4, 16, v17
	v_mul_f32_e32 v4, 0xbfb8aa3b, v4
	v_exp_f32_e32 v18, v18
	v_exp_f32_e32 v4, v4
	v_exp_f32_e32 v5, v5
	v_pk_mul_f32 v[2:3], v[2:3], v[6:7]
	v_add_f32_e32 v18, 1.0, v18
	v_add_f32_e32 v4, 1.0, v4
	v_add_f32_e32 v5, 1.0, v5
	v_rcp_f32_e32 v18, v18
	v_rcp_f32_e32 v4, v4
	v_rcp_f32_e32 v5, v5
	v_pk_mul_f32 v[0:1], v[18:19], v[0:1]
	s_nop 0
	v_cvt_pk_bf16_f32 v0, v0, v1
	v_pk_mul_f32 v[2:3], v[4:5], v[2:3]
	s_nop 0
	v_cvt_pk_bf16_f32 v1, v2, v3
	global_store_dwordx2 v[100:101], v[0:1], off offset:512
	global_load_dwordx2 v[4:5], v[102:103], off offset:3072
	s_nop 0
	global_load_dwordx4 v[0:3], v[188:189], off
	s_waitcnt vmcnt(1)
	v_lshlrev_b32_e32 v6, 16, v4
	v_and_b32_e32 v4, 0xffff0000, v4
	v_mul_f32_e32 v4, 0xbfb8aa3b, v4
	v_exp_f32_e32 v4, v4
	v_mul_f32_e32 v6, 0xbfb8aa3b, v6
	v_exp_f32_e32 v6, v6
	s_waitcnt vmcnt(0)
	v_pk_mul_f32 v[0:1], v[0:1], v[8:9]
	v_add_f32_e32 v4, 1.0, v4
	v_rcp_f32_e32 v7, v4
	v_lshlrev_b32_e32 v4, 16, v5
	v_and_b32_e32 v5, 0xffff0000, v5
	v_mul_f32_e32 v4, 0xbfb8aa3b, v4
	v_mul_f32_e32 v5, 0xbfb8aa3b, v5
	v_exp_f32_e32 v4, v4
	v_exp_f32_e32 v5, v5
	v_add_f32_e32 v6, 1.0, v6
	v_rcp_f32_e32 v6, v6
	v_add_f32_e32 v4, 1.0, v4
	v_add_f32_e32 v5, 1.0, v5
	v_rcp_f32_e32 v4, v4
	v_rcp_f32_e32 v5, v5
	v_pk_mul_f32 v[0:1], v[6:7], v[0:1]
	v_pk_mul_f32 v[6:7], v[66:67], v[32:33] op_sel_hi:[1,0]
	v_cvt_pk_bf16_f32 v0, v0, v1
	v_pk_mul_f32 v[2:3], v[2:3], v[6:7]
	v_pk_mul_f32 v[8:9], v[44:45], v[32:33] op_sel_hi:[1,0]
	v_pk_mul_f32 v[2:3], v[4:5], v[2:3]
	s_nop 0
	v_cvt_pk_bf16_f32 v1, v2, v3
	v_lshl_add_u64 v[2:3], v[12:13], 0, v[184:185]
	global_store_dwordx2 v[2:3], v[0:1], off offset:512
	v_lshl_add_u64 v[0:1], v[14:15], 0, v[206:207]
	global_load_dwordx2 v[4:5], v[0:1], off offset:3072
	s_nop 0
	global_load_dwordx4 v[0:3], v[208:209], off
	s_waitcnt vmcnt(1)
	v_lshlrev_b32_e32 v6, 16, v4
	v_and_b32_e32 v4, 0xffff0000, v4
	v_mul_f32_e32 v4, 0xbfb8aa3b, v4
	v_exp_f32_e32 v4, v4
	v_mul_f32_e32 v6, 0xbfb8aa3b, v6
	v_exp_f32_e32 v6, v6
	s_waitcnt vmcnt(0)
	v_pk_mul_f32 v[0:1], v[0:1], v[8:9]
	v_add_f32_e32 v4, 1.0, v4
	v_rcp_f32_e32 v7, v4
	v_lshlrev_b32_e32 v4, 16, v5
	v_and_b32_e32 v5, 0xffff0000, v5
	v_mul_f32_e32 v4, 0xbfb8aa3b, v4
	v_mul_f32_e32 v5, 0xbfb8aa3b, v5
	v_exp_f32_e32 v4, v4
	v_exp_f32_e32 v5, v5
	v_add_f32_e32 v6, 1.0, v6
	v_rcp_f32_e32 v6, v6
	v_add_f32_e32 v4, 1.0, v4
	v_add_f32_e32 v5, 1.0, v5
	v_rcp_f32_e32 v4, v4
	v_rcp_f32_e32 v5, v5
	v_pk_mul_f32 v[0:1], v[6:7], v[0:1]
	v_pk_mul_f32 v[6:7], v[10:11], v[32:33] op_sel_hi:[1,0]
	v_cvt_pk_bf16_f32 v0, v0, v1
	v_pk_mul_f32 v[2:3], v[2:3], v[6:7]
	s_nop 0
	v_pk_mul_f32 v[2:3], v[4:5], v[2:3]
	s_nop 0
	v_cvt_pk_bf16_f32 v1, v2, v3
	v_lshl_add_u64 v[2:3], v[12:13], 0, v[206:207]
	global_store_dwordx2 v[2:3], v[0:1], off offset:512
	s_waitcnt lgkmcnt(0)
	s_andn2_b64 exec, exec, s[90:91]
	s_cbranch_execnz .LBB0_890
